# static s_setprio 1 for waves 4-7 in mixer-A tile loop; gate/up epilogue rowss loads hoisted
# speedup vs baseline: 1.0100x; 1.0100x over previous
.LBB0_406:
	s_lshl_b32 s2, s6, 4
	v_readlane_b32 s3, v254, 17
	s_add_i32 s2, s3, s2
	s_ashr_i32 s4, s2, 3
	v_mbcnt_lo_u32_b32 v9, -1, 0
	v_mbcnt_hi_u32_b32 v9, -1, v9
	s_ashr_i32 s5, s4, 31
	v_ashrrev_i32_e32 v0, 3, v9
	v_add_u32_e32 v1, s36, v0
	s_lshl_b64 s[2:3], s[4:5], 12
	v_lshrrev_b32_e32 v1, 1, v1
	v_xor_b32_e32 v1, v1, v9
	s_add_i32 s5, s2, s36
	v_lshlrev_b32_e32 v1, 3, v1
	v_add_lshl_u32 v11, s5, v0, 10
	v_readlane_b32 s5, v254, 4
	v_and_b32_e32 v10, 56, v1
	v_ashrrev_i32_e32 v1, 4, v9
	s_add_i32 s5, s5, s2
	v_add_lshl_u32 v13, s5, v1, 10
	v_readlane_b32 s5, v254, 6
	v_and_b32_e32 v2, 15, v9
	v_lshlrev_b32_e32 v3, 2, v1
	s_add_u32 s2, s2, s5
	v_readlane_b32 s5, v254, 7
	v_lshrrev_b32_e32 v1, 4, v9
	v_bitop3_b32 v2, v3, v2, 12 bitop3:0x6c
	s_addc_u32 s3, s3, s5
	v_xor_b32_e32 v4, v1, v9
	v_ashrrev_i32_e32 v1, 31, v0
	v_lshlrev_b32_e32 v12, 3, v2
	v_lshl_add_u64 v[2:3], s[2:3], 0, v[0:1]
	v_lshlrev_b32_e32 v1, 4, v4
	v_and_b32_e32 v160, 0x70, v1
	v_add_u32_e32 v1, 64, v9
	v_ashrrev_i32_e32 v4, 3, v1
	v_lshrrev_b32_e32 v1, 4, v1
	v_ashrrev_i32_e32 v5, 31, v4
	v_xor_b32_e32 v1, v1, v9
	v_lshl_add_u64 v[4:5], s[2:3], 0, v[4:5]
	v_lshlrev_b64 v[4:5], 11, v[4:5]
	v_lshlrev_b32_e32 v1, 4, v1
	v_lshl_add_u64 v[4:5], s[92:93], 0, v[4:5]
	v_and_b32_e32 v6, 0x70, v1
	v_mov_b32_e32 v7, v161
	v_add_u32_e32 v1, 0x80, v9
	v_lshl_add_u64 v[4:5], v[4:5], 0, v[6:7]
	v_ashrrev_i32_e32 v6, 3, v1
	v_add_u32_e32 v1, 0xc0, v9
	v_lshlrev_b64 v[2:3], 11, v[2:3]
	v_readlane_b32 s5, v254, 5
	v_ashrrev_i32_e32 v7, 31, v6
	v_ashrrev_i32_e32 v8, 3, v1
	v_lshrrev_b32_e32 v1, 4, v1
	v_lshl_add_u64 v[2:3], s[92:93], 0, v[2:3]
	s_add_i32 s5, s5, 0
	v_lshl_add_u64 v[6:7], s[2:3], 0, v[6:7]
	v_xor_b32_e32 v1, v1, v9
	v_ashrrev_i32_e32 v9, 31, v8
	v_lshl_add_u64 v[2:3], v[2:3], 0, v[160:161]
	s_add_i32 s7, s5, 0x10000
	s_mov_b32 s8, m0
	s_mov_b32 m0, s7
	s_nop 0
	global_load_lds_dwordx4 v[2:3], off
	s_mov_b32 m0, s8
	v_lshlrev_b64 v[6:7], 11, v[6:7]
	v_lshl_add_u64 v[8:9], s[2:3], 0, v[8:9]
	s_add_i32 s7, s5, 0x10400
	s_mov_b32 s8, m0
	s_mov_b32 m0, s7
	s_nop 0
	global_load_lds_dwordx4 v[4:5], off
	s_mov_b32 m0, s8
	v_lshl_add_u64 v[6:7], s[92:93], 0, v[6:7]
	v_lshlrev_b64 v[8:9], 11, v[8:9]
	v_lshlrev_b32_e32 v1, 4, v1
	v_lshl_add_u64 v[6:7], v[6:7], 0, v[160:161]
	s_add_i32 s7, s5, 0x10800
	s_mov_b32 s8, m0
	s_mov_b32 m0, s7
	s_nop 0
	global_load_lds_dwordx4 v[6:7], off
	s_mov_b32 m0, s8
	v_lshl_add_u64 v[8:9], s[92:93], 0, v[8:9]
	v_and_b32_e32 v160, 0x70, v1
	v_lshl_add_u64 v[8:9], v[8:9], 0, v[160:161]
	s_add_i32 s7, s5, 0x10c00
	s_mov_b32 s8, m0
	s_mov_b32 m0, s7
	s_nop 0
	global_load_lds_dwordx4 v[8:9], off
	s_mov_b32 m0, s8
	v_lshl_add_u64 v[2:3], v[2:3], 0, s[38:39]
	s_add_i32 s7, s5, 0x11000
	s_mov_b32 s8, m0
	s_mov_b32 m0, s7
	s_nop 0
	global_load_lds_dwordx4 v[2:3], off
	s_mov_b32 m0, s8
	v_lshl_add_u64 v[2:3], v[4:5], 0, s[38:39]
	s_add_i32 s7, s5, 0x11400
	s_mov_b32 s8, m0
	s_mov_b32 m0, s7
	s_nop 0
	global_load_lds_dwordx4 v[2:3], off
	s_mov_b32 m0, s8
	v_lshl_add_u64 v[2:3], v[6:7], 0, s[38:39]
	s_add_i32 s7, s5, 0x11800
	s_mov_b32 s8, m0
	s_mov_b32 m0, s7
	s_nop 0
	global_load_lds_dwordx4 v[2:3], off
	s_mov_b32 m0, s8
	v_lshl_add_u64 v[2:3], v[8:9], 0, s[38:39]
	s_add_i32 s5, s5, 0x11c00
	s_mov_b32 s7, m0
	s_mov_b32 m0, s5
	s_nop 0
	global_load_lds_dwordx4 v[2:3], off
	s_mov_b32 m0, s7
	v_or3_b32 v160, v10, v11, s40
	v_lshl_add_u64 v[4:5], v[160:161], 1, s[66:67]
	s_mov_b32 s5, m0
	s_mov_b32 m0, s49
	s_nop 0
	global_load_lds_dwordx4 v[4:5], off
	s_mov_b32 m0, s5
	v_or3_b32 v2, v12, v13, s40
	v_lshl_add_u64 v[4:5], v[4:5], 0, s[38:39]
	s_mov_b32 s5, m0
	s_mov_b32 m0, s33
	s_nop 0
	global_load_lds_dwordx4 v[4:5], off
	s_mov_b32 m0, s5
	v_mov_b32_e32 v3, v161
	v_lshl_add_u64 v[4:5], v[2:3], 1, s[68:69]
	s_mov_b32 s5, m0
	s_mov_b32 m0, s54
	s_nop 0
	global_load_lds_dwordx4 v[4:5], off
	s_mov_b32 m0, s5
	v_add_u32_e32 v160, 0x8000, v2
	v_lshl_add_u64 v[2:3], v[160:161], 1, s[68:69]
	s_mov_b32 s5, m0
	s_mov_b32 m0, s47
	s_nop 0
	global_load_lds_dwordx4 v[2:3], off
	s_mov_b32 m0, s5
	s_lshl_b32 s4, s4, 22
	v_readlane_b32 s5, v255, 1
	s_waitcnt vmcnt(0)
	s_add_i32 s4, s5, s4
	v_lshlrev_b32_e32 v0, 10, v0
	v_or_b32_e32 v1, s40, v13
	v_add3_u32 v202, s4, v0, v10
	v_mov_b32_e32 v0, 0
	v_add_u32_e32 v201, v1, v12
	s_mov_b32 s4, 0
	s_mov_b32 s5, 0
	v_mov_b32_e32 v1, v0
	v_mov_b32_e32 v2, v0
	v_mov_b32_e32 v3, v0
	v_mov_b32_e32 v4, v0
	v_mov_b32_e32 v5, v0
	v_mov_b32_e32 v6, v0
	v_mov_b32_e32 v7, v0
	v_mov_b32_e32 v8, v0
	v_mov_b32_e32 v9, v0
	v_mov_b32_e32 v10, v0
	v_mov_b32_e32 v11, v0
	v_mov_b32_e32 v12, v0
	v_mov_b32_e32 v13, v0
	v_mov_b32_e32 v14, v0
	v_mov_b32_e32 v15, v0
	v_mov_b32_e32 v16, v0
	v_mov_b32_e32 v17, v0
	v_mov_b32_e32 v18, v0
	v_mov_b32_e32 v19, v0
	v_mov_b32_e32 v20, v0
	v_mov_b32_e32 v21, v0
	v_mov_b32_e32 v22, v0
	v_mov_b32_e32 v23, v0
	v_mov_b32_e32 v24, v0
	v_mov_b32_e32 v25, v0
	v_mov_b32_e32 v26, v0
	v_mov_b32_e32 v27, v0
	v_mov_b32_e32 v28, v0
	v_mov_b32_e32 v29, v0
	v_mov_b32_e32 v30, v0
	v_mov_b32_e32 v31, v0
	v_mov_b32_e32 v32, v0
	v_mov_b32_e32 v33, v0
	v_mov_b32_e32 v34, v0
	v_mov_b32_e32 v35, v0
	v_mov_b32_e32 v36, v0
	v_mov_b32_e32 v37, v0
	v_mov_b32_e32 v38, v0
	v_mov_b32_e32 v39, v0
	v_mov_b32_e32 v40, v0
	v_mov_b32_e32 v41, v0
	v_mov_b32_e32 v42, v0
	v_mov_b32_e32 v43, v0
	v_mov_b32_e32 v44, v0
	v_mov_b32_e32 v45, v0
	v_mov_b32_e32 v46, v0
	v_mov_b32_e32 v47, v0
	v_mov_b32_e32 v48, v0
	v_mov_b32_e32 v49, v0
	v_mov_b32_e32 v50, v0
	v_mov_b32_e32 v51, v0
	v_mov_b32_e32 v52, v0
	v_mov_b32_e32 v53, v0
	v_mov_b32_e32 v54, v0
	v_mov_b32_e32 v55, v0
	v_mov_b32_e32 v56, v0
	v_mov_b32_e32 v57, v0
	v_mov_b32_e32 v58, v0
	v_mov_b32_e32 v59, v0
	v_mov_b32_e32 v60, v0
	v_mov_b32_e32 v61, v0
	v_mov_b32_e32 v62, v0
	v_mov_b32_e32 v63, v0
	v_mov_b32_e32 v64, v0
	v_mov_b32_e32 v65, v0
	v_mov_b32_e32 v66, v0
	v_mov_b32_e32 v67, v0
	v_mov_b32_e32 v68, v0
	v_mov_b32_e32 v69, v0
	v_mov_b32_e32 v70, v0
	v_mov_b32_e32 v71, v0
	v_mov_b32_e32 v72, v0
	v_mov_b32_e32 v73, v0
	v_mov_b32_e32 v74, v0
	v_mov_b32_e32 v75, v0
	v_mov_b32_e32 v76, v0
	v_mov_b32_e32 v77, v0
	v_mov_b32_e32 v78, v0
	v_mov_b32_e32 v79, v0
	v_mov_b32_e32 v80, v0
	v_mov_b32_e32 v81, v0
	v_mov_b32_e32 v82, v0
	v_mov_b32_e32 v83, v0
	v_mov_b32_e32 v84, v0
	v_mov_b32_e32 v85, v0
	v_mov_b32_e32 v86, v0
	v_mov_b32_e32 v87, v0
	v_mov_b32_e32 v88, v0
	v_mov_b32_e32 v89, v0
	v_mov_b32_e32 v90, v0
	v_mov_b32_e32 v91, v0
	v_mov_b32_e32 v92, v0
	v_mov_b32_e32 v93, v0
	v_mov_b32_e32 v94, v0
	v_mov_b32_e32 v95, v0
	v_mov_b32_e32 v96, v0
	v_mov_b32_e32 v97, v0
	v_mov_b32_e32 v98, v0
	v_mov_b32_e32 v99, v0
	v_mov_b32_e32 v100, v0
	v_mov_b32_e32 v101, v0
	v_mov_b32_e32 v102, v0
	v_mov_b32_e32 v103, v0
	v_mov_b32_e32 v104, v0
	v_mov_b32_e32 v105, v0
	v_mov_b32_e32 v106, v0
	v_mov_b32_e32 v107, v0
	v_mov_b32_e32 v108, v0
	v_mov_b32_e32 v109, v0
	v_mov_b32_e32 v110, v0
	v_mov_b32_e32 v111, v0
	v_mov_b32_e32 v112, v0
	v_mov_b32_e32 v113, v0
	v_mov_b32_e32 v114, v0
	v_mov_b32_e32 v115, v0
	v_mov_b32_e32 v116, v0
	v_mov_b32_e32 v117, v0
	v_mov_b32_e32 v118, v0
	v_mov_b32_e32 v119, v0
	v_mov_b32_e32 v120, v0
	v_mov_b32_e32 v121, v0
	v_mov_b32_e32 v122, v0
	v_mov_b32_e32 v123, v0
	v_mov_b32_e32 v124, v0
	v_mov_b32_e32 v125, v0
	v_mov_b32_e32 v126, v0
	v_mov_b32_e32 v127, v0
	v_mov_b32_e32 v166, v0
	v_mov_b32_e32 v167, v0
	v_readlane_b32 s98, v253, 39
	s_cmpk_ge_u32 s98, 0x100
	s_cbranch_scc0 .Lattn_prio_skip_a
	s_setprio 1
.Lattn_prio_skip_a:
	s_barrier
	s_branch .LBB0_408

.LBB0_410:
	s_setprio 0
	v_mov_b32_e32 v129, v167
	v_mov_b32_e32 v130, v166
	v_mbcnt_lo_u32_b32 v128, -1, 0
	v_mbcnt_hi_u32_b32 v128, -1, v128
	s_nop 0
	v_permlane32_swap_b32_e32 v167, v129
	v_and_b32_e32 v134, 31, v128
	v_permlane32_swap_b32_e32 v166, v130
	v_cmp_gt_u32_e32 vcc, 32, v128
	s_and_saveexec_b64 s[4:5], vcc
	s_cbranch_execz .LBB0_405
	v_add_f32_e32 v130, v166, v130
	v_add_f32_e32 v129, v167, v129
	v_rcp_f32_e32 v130, v130
	v_rcp_f32_e32 v129, v129
	v_lshl_add_u32 v132, v134, 2, s59
	v_lshl_add_u32 v131, v128, 2, s59
	v_mul_f32_e32 v130, s14, v130
	ds_write_b32 v132, v129
	ds_write_b32 v131, v130 offset:128
	s_branch .LBB0_405

.LBB0_413:
	s_ashr_i32 s4, s7, 7
	v_mbcnt_lo_u32_b32 v9, -1, 0
	v_mbcnt_hi_u32_b32 v9, -1, v9
	s_ashr_i32 s5, s4, 31
	v_ashrrev_i32_e32 v0, 3, v9
	v_add_u32_e32 v1, s36, v0
	s_lshl_b64 s[2:3], s[4:5], 12
	s_lshl_b32 s5, s7, 8
	v_lshrrev_b32_e32 v1, 1, v1
	s_and_b32 s5, s5, 0xf00
	v_readlane_b32 s8, v254, 3
	v_xor_b32_e32 v1, v1, v9
	s_add_i32 s10, s2, s36
	s_add_i32 s5, s5, s8
	s_lshl_b32 s8, s7, 3
	v_lshlrev_b32_e32 v1, 3, v1
	v_add_lshl_u32 v11, s10, v0, 10
	v_readlane_b32 s10, v254, 4
	s_and_b32 s9, s6, 0x380
	s_and_b32 s8, s8, 0x380
	v_and_b32_e32 v10, 56, v1
	v_ashrrev_i32_e32 v1, 4, v9
	s_add_i32 s10, s10, s2
	v_and_b32_e32 v2, 15, v9
	v_lshlrev_b32_e32 v3, 2, v1
	v_add_lshl_u32 v13, s10, v1, 10
	s_add_u32 s2, s2, s5
	v_lshrrev_b32_e32 v1, 4, v9
	v_bitop3_b32 v2, v3, v2, 12 bitop3:0x6c
	s_addc_u32 s3, s3, 0
	v_xor_b32_e32 v4, v1, v9
	v_ashrrev_i32_e32 v1, 31, v0
	v_lshlrev_b32_e32 v12, 3, v2
	v_lshl_add_u64 v[2:3], s[2:3], 0, v[0:1]
	v_lshlrev_b32_e32 v1, 4, v4
	v_and_b32_e32 v160, 0x70, v1
	v_add_u32_e32 v1, 64, v9
	v_ashrrev_i32_e32 v4, 3, v1
	v_ashrrev_i32_e32 v5, 31, v4
	v_lshrrev_b32_e32 v1, 4, v1
	v_lshl_add_u64 v[4:5], s[2:3], 0, v[4:5]
	v_xor_b32_e32 v1, v1, v9
	v_lshlrev_b64 v[4:5], 11, v[4:5]
	s_lshl_b32 s86, s8, 1
	v_lshl_add_u64 v[4:5], s[62:63], 0, v[4:5]
	v_lshlrev_b32_e32 v1, 4, v1
	v_lshl_add_u64 v[4:5], v[4:5], 0, s[86:87]
	v_and_b32_e32 v6, 0x70, v1
	v_mov_b32_e32 v7, v161
	v_add_u32_e32 v1, 0x80, v9
	v_lshl_add_u64 v[4:5], v[4:5], 0, v[6:7]
	v_ashrrev_i32_e32 v6, 3, v1
	v_add_u32_e32 v1, 0xc0, v9
	v_lshlrev_b64 v[2:3], 11, v[2:3]
	v_ashrrev_i32_e32 v7, 31, v6
	v_ashrrev_i32_e32 v8, 3, v1
	v_lshrrev_b32_e32 v1, 4, v1
	v_lshl_add_u64 v[2:3], s[62:63], 0, v[2:3]
	v_readlane_b32 s5, v254, 5
	v_lshl_add_u64 v[6:7], s[2:3], 0, v[6:7]
	v_xor_b32_e32 v1, v1, v9
	v_ashrrev_i32_e32 v9, 31, v8
	v_lshl_add_u64 v[2:3], v[2:3], 0, s[86:87]
	s_add_i32 s5, s5, 0
	v_lshlrev_b64 v[6:7], 11, v[6:7]
	v_lshl_add_u64 v[8:9], s[2:3], 0, v[8:9]
	v_lshl_add_u64 v[2:3], v[2:3], 0, v[160:161]
	s_add_i32 s10, s5, 0x10000
	s_mov_b32 s11, m0
	s_mov_b32 m0, s10
	s_nop 0
	global_load_lds_dwordx4 v[2:3], off
	s_mov_b32 m0, s11
	v_lshl_add_u64 v[6:7], s[62:63], 0, v[6:7]
	v_lshlrev_b64 v[8:9], 11, v[8:9]
	s_add_i32 s10, s5, 0x10400
	s_mov_b32 s11, m0
	s_mov_b32 m0, s10
	s_nop 0
	global_load_lds_dwordx4 v[4:5], off
	s_mov_b32 m0, s11
	v_lshl_add_u64 v[6:7], v[6:7], 0, s[86:87]
	v_lshl_add_u64 v[8:9], s[62:63], 0, v[8:9]
	v_lshlrev_b32_e32 v1, 4, v1
	v_lshl_add_u64 v[6:7], v[6:7], 0, v[160:161]
	s_add_i32 s10, s5, 0x10800
	s_mov_b32 s11, m0
	s_mov_b32 m0, s10
	s_nop 0
	global_load_lds_dwordx4 v[6:7], off
	s_mov_b32 m0, s11
	v_lshl_add_u64 v[8:9], v[8:9], 0, s[86:87]
	v_and_b32_e32 v160, 0x70, v1
	v_lshl_add_u64 v[8:9], v[8:9], 0, v[160:161]
	s_add_i32 s10, s5, 0x10c00
	s_mov_b32 s11, m0
	s_mov_b32 m0, s10
	s_nop 0
	global_load_lds_dwordx4 v[8:9], off
	s_mov_b32 m0, s11
	v_lshl_add_u64 v[2:3], v[2:3], 0, s[38:39]
	s_add_i32 s10, s5, 0x11000
	s_mov_b32 s11, m0
	s_mov_b32 m0, s10
	s_nop 0
	global_load_lds_dwordx4 v[2:3], off
	s_mov_b32 m0, s11
	v_lshl_add_u64 v[2:3], v[4:5], 0, s[38:39]
	s_add_i32 s10, s5, 0x11400
	s_mov_b32 s11, m0
	s_mov_b32 m0, s10
	s_nop 0
	global_load_lds_dwordx4 v[2:3], off
	s_mov_b32 m0, s11
	v_lshl_add_u64 v[2:3], v[6:7], 0, s[38:39]
	s_add_i32 s10, s5, 0x11800
	s_mov_b32 s11, m0
	s_mov_b32 m0, s10
	s_nop 0
	global_load_lds_dwordx4 v[2:3], off
	s_mov_b32 m0, s11
	v_lshl_add_u64 v[2:3], v[8:9], 0, s[38:39]
	s_add_i32 s5, s5, 0x11c00
	s_mov_b32 s10, m0
	s_mov_b32 m0, s5
	s_nop 0
	global_load_lds_dwordx4 v[2:3], off
	s_mov_b32 m0, s10
	v_or3_b32 v160, v10, v11, s8
	v_lshl_add_u64 v[4:5], v[160:161], 1, s[66:67]
	s_mov_b32 s5, m0
	s_mov_b32 m0, s49
	s_nop 0
	global_load_lds_dwordx4 v[4:5], off
	s_mov_b32 m0, s5
	v_or3_b32 v2, v12, v13, s8
	v_lshl_add_u64 v[4:5], v[4:5], 0, s[38:39]
	s_mov_b32 s5, m0
	s_mov_b32 m0, s33
	s_nop 0
	global_load_lds_dwordx4 v[4:5], off
	s_mov_b32 m0, s5
	v_mov_b32_e32 v3, v161
	v_lshl_add_u64 v[4:5], v[2:3], 1, s[68:69]
	s_mov_b32 s5, m0
	s_mov_b32 m0, s54
	s_nop 0
	global_load_lds_dwordx4 v[4:5], off
	s_mov_b32 m0, s5
	v_add_u32_e32 v160, 0x8000, v2
	v_lshl_add_u64 v[2:3], v[160:161], 1, s[68:69]
	s_mov_b32 s5, m0
	s_mov_b32 m0, s47
	s_nop 0
	global_load_lds_dwordx4 v[2:3], off
	s_mov_b32 m0, s5
	s_lshl_b32 s4, s4, 22
	v_readlane_b32 s5, v255, 0
	s_add_i32 s4, s5, s4
	s_waitcnt vmcnt(0)
	v_or3_b32 v201, v13, s9, v12
	v_lshlrev_b32_e32 v0, 10, v0
	s_add_i32 s9, s9, s4
	v_add3_u32 v202, s9, v0, v10
	v_mov_b32_e32 v0, 0
	s_mov_b32 s4, 0
	s_mov_b32 s5, 0
	v_mov_b32_e32 v1, v0
	v_mov_b32_e32 v2, v0
	v_mov_b32_e32 v3, v0
	v_mov_b32_e32 v4, v0
	v_mov_b32_e32 v5, v0
	v_mov_b32_e32 v6, v0
	v_mov_b32_e32 v7, v0
	v_mov_b32_e32 v8, v0
	v_mov_b32_e32 v9, v0
	v_mov_b32_e32 v10, v0
	v_mov_b32_e32 v11, v0
	v_mov_b32_e32 v12, v0
	v_mov_b32_e32 v13, v0
	v_mov_b32_e32 v14, v0
	v_mov_b32_e32 v15, v0
	v_mov_b32_e32 v16, v0
	v_mov_b32_e32 v17, v0
	v_mov_b32_e32 v18, v0
	v_mov_b32_e32 v19, v0
	v_mov_b32_e32 v20, v0
	v_mov_b32_e32 v21, v0
	v_mov_b32_e32 v22, v0
	v_mov_b32_e32 v23, v0
	v_mov_b32_e32 v24, v0
	v_mov_b32_e32 v25, v0
	v_mov_b32_e32 v26, v0
	v_mov_b32_e32 v27, v0
	v_mov_b32_e32 v28, v0
	v_mov_b32_e32 v29, v0
	v_mov_b32_e32 v30, v0
	v_mov_b32_e32 v31, v0
	v_mov_b32_e32 v32, v0
	v_mov_b32_e32 v33, v0
	v_mov_b32_e32 v34, v0
	v_mov_b32_e32 v35, v0
	v_mov_b32_e32 v36, v0
	v_mov_b32_e32 v37, v0
	v_mov_b32_e32 v38, v0
	v_mov_b32_e32 v39, v0
	v_mov_b32_e32 v40, v0
	v_mov_b32_e32 v41, v0
	v_mov_b32_e32 v42, v0
	v_mov_b32_e32 v43, v0
	v_mov_b32_e32 v44, v0
	v_mov_b32_e32 v45, v0
	v_mov_b32_e32 v46, v0
	v_mov_b32_e32 v47, v0
	v_mov_b32_e32 v48, v0
	v_mov_b32_e32 v49, v0
	v_mov_b32_e32 v50, v0
	v_mov_b32_e32 v51, v0
	v_mov_b32_e32 v52, v0
	v_mov_b32_e32 v53, v0
	v_mov_b32_e32 v54, v0
	v_mov_b32_e32 v55, v0
	v_mov_b32_e32 v56, v0
	v_mov_b32_e32 v57, v0
	v_mov_b32_e32 v58, v0
	v_mov_b32_e32 v59, v0
	v_mov_b32_e32 v60, v0
	v_mov_b32_e32 v61, v0
	v_mov_b32_e32 v62, v0
	v_mov_b32_e32 v63, v0
	v_mov_b32_e32 v64, v0
	v_mov_b32_e32 v65, v0
	v_mov_b32_e32 v66, v0
	v_mov_b32_e32 v67, v0
	v_mov_b32_e32 v68, v0
	v_mov_b32_e32 v69, v0
	v_mov_b32_e32 v70, v0
	v_mov_b32_e32 v71, v0
	v_mov_b32_e32 v72, v0
	v_mov_b32_e32 v73, v0
	v_mov_b32_e32 v74, v0
	v_mov_b32_e32 v75, v0
	v_mov_b32_e32 v76, v0
	v_mov_b32_e32 v77, v0
	v_mov_b32_e32 v78, v0
	v_mov_b32_e32 v79, v0
	v_mov_b32_e32 v80, v0
	v_mov_b32_e32 v81, v0
	v_mov_b32_e32 v82, v0
	v_mov_b32_e32 v83, v0
	v_mov_b32_e32 v84, v0
	v_mov_b32_e32 v85, v0
	v_mov_b32_e32 v86, v0
	v_mov_b32_e32 v87, v0
	v_mov_b32_e32 v88, v0
	v_mov_b32_e32 v89, v0
	v_mov_b32_e32 v90, v0
	v_mov_b32_e32 v91, v0
	v_mov_b32_e32 v92, v0
	v_mov_b32_e32 v93, v0
	v_mov_b32_e32 v94, v0
	v_mov_b32_e32 v95, v0
	v_mov_b32_e32 v96, v0
	v_mov_b32_e32 v97, v0
	v_mov_b32_e32 v98, v0
	v_mov_b32_e32 v99, v0
	v_mov_b32_e32 v100, v0
	v_mov_b32_e32 v101, v0
	v_mov_b32_e32 v102, v0
	v_mov_b32_e32 v103, v0
	v_mov_b32_e32 v104, v0
	v_mov_b32_e32 v105, v0
	v_mov_b32_e32 v106, v0
	v_mov_b32_e32 v107, v0
	v_mov_b32_e32 v108, v0
	v_mov_b32_e32 v109, v0
	v_mov_b32_e32 v110, v0
	v_mov_b32_e32 v111, v0
	v_mov_b32_e32 v112, v0
	v_mov_b32_e32 v113, v0
	v_mov_b32_e32 v114, v0
	v_mov_b32_e32 v115, v0
	v_mov_b32_e32 v116, v0
	v_mov_b32_e32 v117, v0
	v_mov_b32_e32 v118, v0
	v_mov_b32_e32 v119, v0
	v_mov_b32_e32 v120, v0
	v_mov_b32_e32 v121, v0
	v_mov_b32_e32 v122, v0
	v_mov_b32_e32 v123, v0
	v_mov_b32_e32 v124, v0
	v_mov_b32_e32 v125, v0
	v_mov_b32_e32 v126, v0
	v_mov_b32_e32 v127, v0
	v_mov_b32_e32 v166, v0
	v_mov_b32_e32 v167, v0
	v_readlane_b32 s98, v253, 39
	s_cmpk_ge_u32 s98, 0x100
	s_cbranch_scc0 .Lattn_prio_skip_b
	s_setprio 1

.LBB0_482:
	s_ashr_i32 s13, s2, 4
	v_lshl_or_b32 v158, s3, 8, v168
	s_mul_hi_i32 s3, s13, 0x7400
	s_mulk_i32 s13, 0x7400
	s_add_u32 s20, s35, s13
	v_ashrrev_i32_e32 v159, 31, v158
	s_addc_u32 s21, s84, s3
	v_lshlrev_b64 v[138:139], 2, v[158:159]
	v_lshl_add_u64 v[162:163], s[20:21], 0, v[138:139]
	v_lshl_add_u64 v[174:175], s[8:9], 0, v[138:139]
	global_load_dwordx4 v[138:141], v[162:163], off offset:16
	global_load_dwordx4 v[142:145], v[162:163], off
	global_load_dwordx4 v[154:157], v[174:175], off offset:16
	global_load_dwordx4 v[146:149], v[174:175], off
	global_load_dwordx4 v[178:181], v[162:163], off offset:528
	global_load_dwordx4 v[182:185], v[162:163], off offset:512
	global_load_dwordx4 v[170:173], v[174:175], off offset:528
	v_lshl_add_u32 v186, s2, 8, v166
	v_ashrrev_i32_e32 v187, 31, v186
	v_lshl_add_u64 v[186:187], v[186:187], 2, s[42:43]
	global_load_dword v188, v[186:187], off
	global_load_dword v189, v[186:187], off offset:64
	global_load_dword v190, v[186:187], off offset:128
	global_load_dword v191, v[186:187], off offset:192
	global_load_dword v192, v[186:187], off offset:512
	global_load_dword v193, v[186:187], off offset:576
	global_load_dword v194, v[186:187], off offset:640
	global_load_dword v195, v[186:187], off offset:704
	global_load_dwordx4 v[174:177], v[174:175], off offset:512
	s_mov_b64 s[20:21], -1
	s_andn2_b64 vcc, exec, s[4:5]
	s_waitcnt vmcnt(0)
	v_pk_add_f32 v[150:151], v[144:145], v[148:149]
	v_pk_add_f32 v[152:153], v[142:143], v[146:147]
	v_pk_add_f32 v[146:147], v[140:141], v[156:157]
	v_pk_add_f32 v[148:149], v[138:139], v[154:155]
	v_pk_add_f32 v[144:145], v[182:183], v[174:175]
	v_pk_add_f32 v[138:139], v[180:181], v[172:173]
	v_lshl_add_u32 v156, s2, 8, v166
	v_ashrrev_i32_e32 v157, 31, v156
	v_pk_add_f32 v[142:143], v[184:185], v[176:177]
	v_pk_add_f32 v[140:141], v[178:179], v[170:171]
	v_lshl_add_u64 v[154:155], v[156:157], 2, s[42:43]
	v_fmamk_f32 v162, v188, 0x3a800000, v204
	v_rsq_f32_e32 v170, v162
	v_lshlrev_b64 v[162:163], 11, v[156:157]
	v_fma_f32 v124, v124, v170, v152
	v_fma_f32 v125, v125, v170, v153
	v_fma_f32 v126, v126, v170, v150
	v_fma_f32 v127, v127, v170, v151
	v_fma_f32 v120, v120, v170, v148
	v_fma_f32 v121, v121, v170, v149
	v_fma_f32 v122, v122, v170, v146
	v_fma_f32 v123, v123, v170, v147
	v_mul_f32_e32 v124, 0xbfb8aa3b, v124
	v_mul_f32_e32 v125, 0xbfb8aa3b, v125
	v_mul_f32_e32 v126, 0xbfb8aa3b, v126
	v_mul_f32_e32 v127, 0xbfb8aa3b, v127
	v_mul_f32_e32 v120, 0xbfb8aa3b, v120
	v_mul_f32_e32 v121, 0xbfb8aa3b, v121
	v_mul_f32_e32 v122, 0xbfb8aa3b, v122
	v_mul_f32_e32 v123, 0xbfb8aa3b, v123
	v_exp_f32_e32 v124, v124
	v_exp_f32_e32 v125, v125
	v_exp_f32_e32 v126, v126
	v_exp_f32_e32 v127, v127
	v_exp_f32_e32 v120, v120
	v_exp_f32_e32 v121, v121
	v_exp_f32_e32 v122, v122
	v_exp_f32_e32 v123, v123
	v_fma_f32 v112, v112, v170, v140
	v_mul_f32_e32 v112, 0xbfb8aa3b, v112
	v_exp_f32_e32 v112, v112
	v_add_f32_e32 v124, 1.0, v124
	v_add_f32_e32 v125, 1.0, v125
	v_add_f32_e32 v126, 1.0, v126
	v_add_f32_e32 v127, 1.0, v127
	v_add_f32_e32 v120, 1.0, v120
	v_add_f32_e32 v121, 1.0, v121
	v_add_f32_e32 v122, 1.0, v122
	v_add_f32_e32 v123, 1.0, v123
	v_rcp_f32_e32 v124, v124
	v_rcp_f32_e32 v125, v125
	v_rcp_f32_e32 v126, v126
	v_rcp_f32_e32 v127, v127
	v_rcp_f32_e32 v120, v120
	v_rcp_f32_e32 v121, v121
	v_rcp_f32_e32 v122, v122
	v_rcp_f32_e32 v123, v123
	v_cvt_pk_bf16_f32 v124, v124, v125
	v_cvt_pk_bf16_f32 v125, v126, v127
	v_cvt_pk_bf16_f32 v126, v120, v121
	v_cvt_pk_bf16_f32 v127, v122, v123
	v_lshl_add_u64 v[122:123], s[66:67], 0, v[162:163]
	v_lshlrev_b64 v[120:121], 1, v[158:159]
	v_lshl_add_u64 v[122:123], v[122:123], 0, v[120:121]
	v_add_f32_e32 v112, 1.0, v112
	global_store_dwordx4 v[122:123], v[124:127], off
	v_fma_f32 v116, v116, v170, v144
	v_fma_f32 v117, v117, v170, v145
	v_rcp_f32_e32 v124, v112
	v_fma_f32 v112, v113, v170, v141
	v_mul_f32_e32 v112, 0xbfb8aa3b, v112
	v_exp_f32_e32 v112, v112
	v_fma_f32 v118, v118, v170, v142
	v_fma_f32 v119, v119, v170, v143
	v_mul_f32_e32 v116, 0xbfb8aa3b, v116
	v_add_f32_e32 v112, 1.0, v112
	v_rcp_f32_e32 v125, v112
	v_fma_f32 v112, v114, v170, v138
	v_mul_f32_e32 v112, 0xbfb8aa3b, v112
	v_exp_f32_e32 v112, v112
	v_mul_f32_e32 v117, 0xbfb8aa3b, v117
	v_mul_f32_e32 v118, 0xbfb8aa3b, v118
	v_mul_f32_e32 v119, 0xbfb8aa3b, v119
	v_add_f32_e32 v112, 1.0, v112
	v_rcp_f32_e32 v126, v112
	v_fma_f32 v112, v115, v170, v139
	v_mul_f32_e32 v112, 0xbfb8aa3b, v112
	v_exp_f32_e32 v112, v112
	v_exp_f32_e32 v116, v116
	v_exp_f32_e32 v117, v117
	v_exp_f32_e32 v118, v118
	v_exp_f32_e32 v119, v119
	v_add_f32_e32 v112, 1.0, v112
	v_add_f32_e32 v116, 1.0, v116
	v_add_f32_e32 v117, 1.0, v117
	v_add_f32_e32 v118, 1.0, v118
	v_add_f32_e32 v119, 1.0, v119
	v_rcp_f32_e32 v115, v112
	v_rcp_f32_e32 v116, v116
	v_rcp_f32_e32 v117, v117
	v_rcp_f32_e32 v118, v118
	v_rcp_f32_e32 v119, v119
	v_cvt_pk_bf16_f32 v112, v116, v117
	v_cvt_pk_bf16_f32 v113, v118, v119
	v_cvt_pk_bf16_f32 v114, v124, v125
	v_cvt_pk_bf16_f32 v115, v126, v115
	global_store_dwordx4 v[122:123], v[112:115], off offset:256
	s_nop 0
	s_nop 0
	v_or_b32_e32 v114, 16, v156
	v_ashrrev_i32_e32 v115, 31, v114
	v_lshlrev_b64 v[114:115], 11, v[114:115]
	v_fmamk_f32 v112, v189, 0x3a800000, v204
	v_rsq_f32_e32 v112, v112
	s_nop 0
	v_fma_f32 v106, v106, v112, v146
	v_mul_f32_e32 v106, 0xbfb8aa3b, v106
	v_exp_f32_e32 v106, v106
	v_fma_f32 v108, v108, v112, v152
	v_fma_f32 v104, v104, v112, v148
	v_fma_f32 v105, v105, v112, v149
	v_add_f32_e32 v106, 1.0, v106
	v_mul_f32_e32 v108, 0xbfb8aa3b, v108
	v_fma_f32 v109, v109, v112, v153
	v_fma_f32 v110, v110, v112, v150
	v_fma_f32 v111, v111, v112, v151
	v_mul_f32_e32 v104, 0xbfb8aa3b, v104
	v_mul_f32_e32 v105, 0xbfb8aa3b, v105
	v_rcp_f32_e32 v113, v106
	v_fma_f32 v106, v107, v112, v147
	v_exp_f32_e32 v108, v108
	v_mul_f32_e32 v109, 0xbfb8aa3b, v109
	v_mul_f32_e32 v110, 0xbfb8aa3b, v110
	v_mul_f32_e32 v111, 0xbfb8aa3b, v111
	v_exp_f32_e32 v104, v104
	v_exp_f32_e32 v105, v105
	v_mul_f32_e32 v106, 0xbfb8aa3b, v106
	v_exp_f32_e32 v109, v109
	v_exp_f32_e32 v110, v110
	v_exp_f32_e32 v111, v111
	v_exp_f32_e32 v106, v106
	v_fma_f32 v96, v96, v112, v140
	v_mul_f32_e32 v96, 0xbfb8aa3b, v96
	v_exp_f32_e32 v96, v96
	v_add_f32_e32 v108, 1.0, v108
	v_add_f32_e32 v104, 1.0, v104
	v_add_f32_e32 v105, 1.0, v105
	v_rcp_f32_e32 v108, v108
	v_add_f32_e32 v109, 1.0, v109
	v_add_f32_e32 v110, 1.0, v110
	v_add_f32_e32 v111, 1.0, v111
	v_rcp_f32_e32 v104, v104
	v_rcp_f32_e32 v105, v105
	v_add_f32_e32 v106, 1.0, v106
	v_rcp_f32_e32 v109, v109
	v_rcp_f32_e32 v110, v110
	v_rcp_f32_e32 v111, v111
	v_rcp_f32_e32 v116, v106
	v_cvt_pk_bf16_f32 v106, v108, v109
	v_cvt_pk_bf16_f32 v107, v110, v111
	v_cvt_pk_bf16_f32 v108, v104, v105
	v_lshl_add_u64 v[104:105], s[66:67], 0, v[114:115]
	v_lshl_add_u64 v[104:105], v[104:105], 0, v[120:121]
	v_add_f32_e32 v96, 1.0, v96
	v_cvt_pk_bf16_f32 v109, v113, v116
	global_store_dwordx4 v[104:105], v[106:109], off
	v_fma_f32 v100, v100, v112, v144
	v_fma_f32 v101, v101, v112, v145
	v_rcp_f32_e32 v106, v96
	v_fma_f32 v96, v97, v112, v141
	v_mul_f32_e32 v96, 0xbfb8aa3b, v96
	v_exp_f32_e32 v96, v96
	v_fma_f32 v102, v102, v112, v142
	v_fma_f32 v103, v103, v112, v143
	v_mul_f32_e32 v100, 0xbfb8aa3b, v100
	v_add_f32_e32 v96, 1.0, v96
	v_rcp_f32_e32 v107, v96
	v_fma_f32 v96, v98, v112, v138
	v_mul_f32_e32 v96, 0xbfb8aa3b, v96
	v_exp_f32_e32 v96, v96
	v_mul_f32_e32 v101, 0xbfb8aa3b, v101
	v_mul_f32_e32 v102, 0xbfb8aa3b, v102
	v_mul_f32_e32 v103, 0xbfb8aa3b, v103
	v_add_f32_e32 v96, 1.0, v96
	v_rcp_f32_e32 v108, v96
	v_fma_f32 v96, v99, v112, v139
	v_mul_f32_e32 v96, 0xbfb8aa3b, v96
	v_exp_f32_e32 v96, v96
	v_exp_f32_e32 v100, v100
	v_exp_f32_e32 v101, v101
	v_exp_f32_e32 v102, v102
	v_exp_f32_e32 v103, v103
	v_add_f32_e32 v96, 1.0, v96
	v_add_f32_e32 v100, 1.0, v100
	v_add_f32_e32 v101, 1.0, v101
	v_add_f32_e32 v102, 1.0, v102
	v_add_f32_e32 v103, 1.0, v103
	v_rcp_f32_e32 v99, v96
	v_rcp_f32_e32 v100, v100
	v_rcp_f32_e32 v101, v101
	v_rcp_f32_e32 v102, v102
	v_rcp_f32_e32 v103, v103
	v_cvt_pk_bf16_f32 v96, v100, v101
	v_cvt_pk_bf16_f32 v97, v102, v103
	v_cvt_pk_bf16_f32 v98, v106, v107
	v_cvt_pk_bf16_f32 v99, v108, v99
	global_store_dwordx4 v[104:105], v[96:99], off offset:256
	s_nop 0
	s_nop 0
	v_or_b32_e32 v98, 32, v156
	v_ashrrev_i32_e32 v99, 31, v98
	v_lshlrev_b64 v[98:99], 11, v[98:99]
	v_fmamk_f32 v96, v190, 0x3a800000, v204
	v_rsq_f32_e32 v96, v96
	s_nop 0
	v_fma_f32 v90, v90, v96, v146
	v_mul_f32_e32 v90, 0xbfb8aa3b, v90
	v_exp_f32_e32 v90, v90
	v_fma_f32 v92, v92, v96, v152
	v_fma_f32 v88, v88, v96, v148
	v_fma_f32 v89, v89, v96, v149
	v_add_f32_e32 v90, 1.0, v90
	v_mul_f32_e32 v92, 0xbfb8aa3b, v92
	v_fma_f32 v93, v93, v96, v153
	v_fma_f32 v94, v94, v96, v150
	v_fma_f32 v95, v95, v96, v151
	v_mul_f32_e32 v88, 0xbfb8aa3b, v88
	v_mul_f32_e32 v89, 0xbfb8aa3b, v89
	v_rcp_f32_e32 v97, v90
	v_fma_f32 v90, v91, v96, v147
	v_exp_f32_e32 v92, v92
	v_mul_f32_e32 v93, 0xbfb8aa3b, v93
	v_mul_f32_e32 v94, 0xbfb8aa3b, v94
	v_mul_f32_e32 v95, 0xbfb8aa3b, v95
	v_exp_f32_e32 v88, v88
	v_exp_f32_e32 v89, v89
	v_mul_f32_e32 v90, 0xbfb8aa3b, v90
	v_exp_f32_e32 v93, v93
	v_exp_f32_e32 v94, v94
	v_exp_f32_e32 v95, v95
	v_exp_f32_e32 v90, v90
	v_fma_f32 v80, v80, v96, v140
	v_mul_f32_e32 v80, 0xbfb8aa3b, v80
	v_exp_f32_e32 v80, v80
	v_add_f32_e32 v92, 1.0, v92
	v_add_f32_e32 v88, 1.0, v88
	v_add_f32_e32 v89, 1.0, v89
	v_rcp_f32_e32 v92, v92
	v_add_f32_e32 v93, 1.0, v93
	v_add_f32_e32 v94, 1.0, v94
	v_add_f32_e32 v95, 1.0, v95
	v_rcp_f32_e32 v88, v88
	v_rcp_f32_e32 v89, v89
	v_add_f32_e32 v90, 1.0, v90
	v_rcp_f32_e32 v93, v93
	v_rcp_f32_e32 v94, v94
	v_rcp_f32_e32 v95, v95
	v_rcp_f32_e32 v100, v90
	v_cvt_pk_bf16_f32 v90, v92, v93
	v_cvt_pk_bf16_f32 v91, v94, v95
	v_cvt_pk_bf16_f32 v92, v88, v89
	v_lshl_add_u64 v[88:89], s[66:67], 0, v[98:99]
	v_lshl_add_u64 v[88:89], v[88:89], 0, v[120:121]
	v_add_f32_e32 v80, 1.0, v80
	v_cvt_pk_bf16_f32 v93, v97, v100
	global_store_dwordx4 v[88:89], v[90:93], off
	v_fma_f32 v84, v84, v96, v144
	v_fma_f32 v85, v85, v96, v145
	v_rcp_f32_e32 v90, v80
	v_fma_f32 v80, v81, v96, v141
	v_mul_f32_e32 v80, 0xbfb8aa3b, v80
	v_exp_f32_e32 v80, v80
	v_fma_f32 v86, v86, v96, v142
	v_fma_f32 v87, v87, v96, v143
	v_mul_f32_e32 v84, 0xbfb8aa3b, v84
	v_add_f32_e32 v80, 1.0, v80
	v_rcp_f32_e32 v91, v80
	v_fma_f32 v80, v82, v96, v138
	v_mul_f32_e32 v80, 0xbfb8aa3b, v80
	v_exp_f32_e32 v80, v80
	v_mul_f32_e32 v85, 0xbfb8aa3b, v85
	v_mul_f32_e32 v86, 0xbfb8aa3b, v86
	v_mul_f32_e32 v87, 0xbfb8aa3b, v87
	v_add_f32_e32 v80, 1.0, v80
	v_rcp_f32_e32 v92, v80
	v_fma_f32 v80, v83, v96, v139
	v_mul_f32_e32 v80, 0xbfb8aa3b, v80
	v_exp_f32_e32 v80, v80
	v_exp_f32_e32 v84, v84
	v_exp_f32_e32 v85, v85
	v_exp_f32_e32 v86, v86
	v_exp_f32_e32 v87, v87
	v_add_f32_e32 v80, 1.0, v80
	v_add_f32_e32 v84, 1.0, v84
	v_add_f32_e32 v85, 1.0, v85
	v_add_f32_e32 v86, 1.0, v86
	v_add_f32_e32 v87, 1.0, v87
	v_rcp_f32_e32 v83, v80
	v_rcp_f32_e32 v84, v84
	v_rcp_f32_e32 v85, v85
	v_rcp_f32_e32 v86, v86
	v_rcp_f32_e32 v87, v87
	v_cvt_pk_bf16_f32 v80, v84, v85
	v_cvt_pk_bf16_f32 v81, v86, v87
	v_cvt_pk_bf16_f32 v82, v90, v91
	v_cvt_pk_bf16_f32 v83, v92, v83
	global_store_dwordx4 v[88:89], v[80:83], off offset:256
	s_nop 0
	s_nop 0
	v_or_b32_e32 v82, 48, v156
	v_ashrrev_i32_e32 v83, 31, v82
	v_lshlrev_b64 v[82:83], 11, v[82:83]
	v_fmamk_f32 v80, v191, 0x3a800000, v204
	v_rsq_f32_e32 v80, v80
	s_nop 0
	v_fma_f32 v74, v74, v80, v146
	v_mul_f32_e32 v74, 0xbfb8aa3b, v74
	v_exp_f32_e32 v74, v74
	v_fma_f32 v76, v76, v80, v152
	v_fma_f32 v72, v72, v80, v148
	v_fma_f32 v73, v73, v80, v149
	v_add_f32_e32 v74, 1.0, v74
	v_mul_f32_e32 v76, 0xbfb8aa3b, v76
	v_fma_f32 v77, v77, v80, v153
	v_fma_f32 v78, v78, v80, v150
	v_fma_f32 v79, v79, v80, v151
	v_mul_f32_e32 v72, 0xbfb8aa3b, v72
	v_mul_f32_e32 v73, 0xbfb8aa3b, v73
	v_rcp_f32_e32 v81, v74
	v_fma_f32 v74, v75, v80, v147
	v_exp_f32_e32 v76, v76
	v_mul_f32_e32 v77, 0xbfb8aa3b, v77
	v_mul_f32_e32 v78, 0xbfb8aa3b, v78
	v_mul_f32_e32 v79, 0xbfb8aa3b, v79
	v_exp_f32_e32 v72, v72
	v_exp_f32_e32 v73, v73
	v_mul_f32_e32 v74, 0xbfb8aa3b, v74
	v_exp_f32_e32 v77, v77
	v_exp_f32_e32 v78, v78
	v_exp_f32_e32 v79, v79
	v_exp_f32_e32 v74, v74
	v_fma_f32 v64, v64, v80, v140
	v_mul_f32_e32 v64, 0xbfb8aa3b, v64
	v_exp_f32_e32 v64, v64
	v_add_f32_e32 v76, 1.0, v76
	v_add_f32_e32 v72, 1.0, v72
	v_add_f32_e32 v73, 1.0, v73
	v_rcp_f32_e32 v76, v76
	v_add_f32_e32 v77, 1.0, v77
	v_add_f32_e32 v78, 1.0, v78
	v_add_f32_e32 v79, 1.0, v79
	v_rcp_f32_e32 v72, v72
	v_rcp_f32_e32 v73, v73
	v_add_f32_e32 v74, 1.0, v74
	v_rcp_f32_e32 v77, v77
	v_rcp_f32_e32 v78, v78
	v_rcp_f32_e32 v79, v79
	v_rcp_f32_e32 v84, v74
	v_cvt_pk_bf16_f32 v74, v76, v77
	v_cvt_pk_bf16_f32 v75, v78, v79
	v_cvt_pk_bf16_f32 v76, v72, v73
	v_lshl_add_u64 v[72:73], s[66:67], 0, v[82:83]
	v_lshl_add_u64 v[72:73], v[72:73], 0, v[120:121]
	v_add_f32_e32 v64, 1.0, v64
	v_cvt_pk_bf16_f32 v77, v81, v84
	global_store_dwordx4 v[72:73], v[74:77], off
	v_fma_f32 v68, v68, v80, v144
	v_fma_f32 v69, v69, v80, v145
	v_rcp_f32_e32 v74, v64
	v_fma_f32 v64, v65, v80, v141
	v_mul_f32_e32 v64, 0xbfb8aa3b, v64
	v_exp_f32_e32 v64, v64
	v_fma_f32 v70, v70, v80, v142
	v_fma_f32 v71, v71, v80, v143
	v_mul_f32_e32 v68, 0xbfb8aa3b, v68
	v_add_f32_e32 v64, 1.0, v64
	v_rcp_f32_e32 v75, v64
	v_fma_f32 v64, v66, v80, v138
	v_mul_f32_e32 v64, 0xbfb8aa3b, v64
	v_exp_f32_e32 v64, v64
	v_mul_f32_e32 v69, 0xbfb8aa3b, v69
	v_mul_f32_e32 v70, 0xbfb8aa3b, v70
	v_mul_f32_e32 v71, 0xbfb8aa3b, v71
	v_add_f32_e32 v64, 1.0, v64
	v_rcp_f32_e32 v76, v64
	v_fma_f32 v64, v67, v80, v139
	v_mul_f32_e32 v64, 0xbfb8aa3b, v64
	v_exp_f32_e32 v64, v64
	v_exp_f32_e32 v68, v68
	v_exp_f32_e32 v69, v69
	v_exp_f32_e32 v70, v70
	v_exp_f32_e32 v71, v71
	v_add_f32_e32 v64, 1.0, v64
	v_add_f32_e32 v68, 1.0, v68
	v_add_f32_e32 v69, 1.0, v69
	v_add_f32_e32 v70, 1.0, v70
	v_add_f32_e32 v71, 1.0, v71
	v_rcp_f32_e32 v67, v64
	v_rcp_f32_e32 v68, v68
	v_rcp_f32_e32 v69, v69
	v_rcp_f32_e32 v70, v70
	v_rcp_f32_e32 v71, v71
	v_cvt_pk_bf16_f32 v64, v68, v69
	v_cvt_pk_bf16_f32 v65, v70, v71
	v_cvt_pk_bf16_f32 v66, v74, v75
	v_cvt_pk_bf16_f32 v67, v76, v67
	global_store_dwordx4 v[72:73], v[64:67], off offset:256
	s_nop 0
	s_nop 0
	v_add_u32_e32 v66, 0x80, v156
	v_ashrrev_i32_e32 v67, 31, v66
	v_lshlrev_b64 v[66:67], 11, v[66:67]
	v_fmamk_f32 v64, v192, 0x3a800000, v204
	v_rsq_f32_e32 v64, v64
	s_nop 0
	v_fma_f32 v58, v58, v64, v146
	v_mul_f32_e32 v58, 0xbfb8aa3b, v58
	v_exp_f32_e32 v58, v58
	v_fma_f32 v60, v60, v64, v152
	v_fma_f32 v56, v56, v64, v148
	v_fma_f32 v57, v57, v64, v149
	v_add_f32_e32 v58, 1.0, v58
	v_mul_f32_e32 v60, 0xbfb8aa3b, v60
	v_fma_f32 v61, v61, v64, v153
	v_fma_f32 v62, v62, v64, v150
	v_fma_f32 v63, v63, v64, v151
	v_mul_f32_e32 v56, 0xbfb8aa3b, v56
	v_mul_f32_e32 v57, 0xbfb8aa3b, v57
	v_rcp_f32_e32 v65, v58
	v_fma_f32 v58, v59, v64, v147
	v_exp_f32_e32 v60, v60
	v_mul_f32_e32 v61, 0xbfb8aa3b, v61
	v_mul_f32_e32 v62, 0xbfb8aa3b, v62
	v_mul_f32_e32 v63, 0xbfb8aa3b, v63
	v_exp_f32_e32 v56, v56
	v_exp_f32_e32 v57, v57
	v_mul_f32_e32 v58, 0xbfb8aa3b, v58
	v_exp_f32_e32 v61, v61
	v_exp_f32_e32 v62, v62
	v_exp_f32_e32 v63, v63
	v_exp_f32_e32 v58, v58
	v_fma_f32 v48, v48, v64, v140
	v_mul_f32_e32 v48, 0xbfb8aa3b, v48
	v_exp_f32_e32 v48, v48
	v_add_f32_e32 v60, 1.0, v60
	v_add_f32_e32 v56, 1.0, v56
	v_add_f32_e32 v57, 1.0, v57
	v_rcp_f32_e32 v60, v60
	v_add_f32_e32 v61, 1.0, v61
	v_add_f32_e32 v62, 1.0, v62
	v_add_f32_e32 v63, 1.0, v63
	v_rcp_f32_e32 v56, v56
	v_rcp_f32_e32 v57, v57
	v_add_f32_e32 v58, 1.0, v58
	v_rcp_f32_e32 v61, v61
	v_rcp_f32_e32 v62, v62
	v_rcp_f32_e32 v63, v63
	v_rcp_f32_e32 v68, v58
	v_cvt_pk_bf16_f32 v58, v60, v61
	v_cvt_pk_bf16_f32 v59, v62, v63
	v_cvt_pk_bf16_f32 v60, v56, v57
	v_lshl_add_u64 v[56:57], s[66:67], 0, v[66:67]
	v_lshl_add_u64 v[56:57], v[56:57], 0, v[120:121]
	v_add_f32_e32 v48, 1.0, v48
	v_cvt_pk_bf16_f32 v61, v65, v68
	global_store_dwordx4 v[56:57], v[58:61], off
	v_fma_f32 v52, v52, v64, v144
	v_fma_f32 v53, v53, v64, v145
	v_rcp_f32_e32 v58, v48
	v_fma_f32 v48, v49, v64, v141
	v_mul_f32_e32 v48, 0xbfb8aa3b, v48
	v_exp_f32_e32 v48, v48
	v_fma_f32 v54, v54, v64, v142
	v_fma_f32 v55, v55, v64, v143
	v_mul_f32_e32 v52, 0xbfb8aa3b, v52
	v_add_f32_e32 v48, 1.0, v48
	v_rcp_f32_e32 v59, v48
	v_fma_f32 v48, v50, v64, v138
	v_mul_f32_e32 v48, 0xbfb8aa3b, v48
	v_exp_f32_e32 v48, v48
	v_mul_f32_e32 v53, 0xbfb8aa3b, v53
	v_mul_f32_e32 v54, 0xbfb8aa3b, v54
	v_mul_f32_e32 v55, 0xbfb8aa3b, v55
	v_add_f32_e32 v48, 1.0, v48
	v_rcp_f32_e32 v60, v48
	v_fma_f32 v48, v51, v64, v139
	v_mul_f32_e32 v48, 0xbfb8aa3b, v48
	v_exp_f32_e32 v48, v48
	v_exp_f32_e32 v52, v52
	v_exp_f32_e32 v53, v53
	v_exp_f32_e32 v54, v54
	v_exp_f32_e32 v55, v55
	v_add_f32_e32 v48, 1.0, v48
	v_add_f32_e32 v52, 1.0, v52
	v_add_f32_e32 v53, 1.0, v53
	v_add_f32_e32 v54, 1.0, v54
	v_add_f32_e32 v55, 1.0, v55
	v_rcp_f32_e32 v51, v48
	v_rcp_f32_e32 v52, v52
	v_rcp_f32_e32 v53, v53
	v_rcp_f32_e32 v54, v54
	v_rcp_f32_e32 v55, v55
	v_cvt_pk_bf16_f32 v48, v52, v53
	v_cvt_pk_bf16_f32 v49, v54, v55
	v_cvt_pk_bf16_f32 v50, v58, v59
	v_cvt_pk_bf16_f32 v51, v60, v51
	global_store_dwordx4 v[56:57], v[48:51], off offset:256
	s_nop 0
	s_nop 0
	v_add_u32_e32 v50, 0x90, v156
	v_ashrrev_i32_e32 v51, 31, v50
	v_lshlrev_b64 v[50:51], 11, v[50:51]
	v_fmamk_f32 v48, v193, 0x3a800000, v204
	v_rsq_f32_e32 v48, v48
	s_nop 0
	v_fma_f32 v42, v42, v48, v146
	v_mul_f32_e32 v42, 0xbfb8aa3b, v42
	v_exp_f32_e32 v42, v42
	v_fma_f32 v44, v44, v48, v152
	v_fma_f32 v40, v40, v48, v148
	v_fma_f32 v41, v41, v48, v149
	v_add_f32_e32 v42, 1.0, v42
	v_mul_f32_e32 v44, 0xbfb8aa3b, v44
	v_fma_f32 v45, v45, v48, v153
	v_fma_f32 v46, v46, v48, v150
	v_fma_f32 v47, v47, v48, v151
	v_mul_f32_e32 v40, 0xbfb8aa3b, v40
	v_mul_f32_e32 v41, 0xbfb8aa3b, v41
	v_rcp_f32_e32 v49, v42
	v_fma_f32 v42, v43, v48, v147
	v_exp_f32_e32 v44, v44
	v_mul_f32_e32 v45, 0xbfb8aa3b, v45
	v_mul_f32_e32 v46, 0xbfb8aa3b, v46
	v_mul_f32_e32 v47, 0xbfb8aa3b, v47
	v_exp_f32_e32 v40, v40
	v_exp_f32_e32 v41, v41
	v_mul_f32_e32 v42, 0xbfb8aa3b, v42
	v_exp_f32_e32 v45, v45
	v_exp_f32_e32 v46, v46
	v_exp_f32_e32 v47, v47
	v_exp_f32_e32 v42, v42
	v_fma_f32 v32, v32, v48, v140
	v_mul_f32_e32 v32, 0xbfb8aa3b, v32
	v_exp_f32_e32 v32, v32
	v_add_f32_e32 v44, 1.0, v44
	v_add_f32_e32 v40, 1.0, v40
	v_add_f32_e32 v41, 1.0, v41
	v_rcp_f32_e32 v44, v44
	v_add_f32_e32 v45, 1.0, v45
	v_add_f32_e32 v46, 1.0, v46
	v_add_f32_e32 v47, 1.0, v47
	v_rcp_f32_e32 v40, v40
	v_rcp_f32_e32 v41, v41
	v_add_f32_e32 v42, 1.0, v42
	v_rcp_f32_e32 v45, v45
	v_rcp_f32_e32 v46, v46
	v_rcp_f32_e32 v47, v47
	v_rcp_f32_e32 v52, v42
	v_cvt_pk_bf16_f32 v42, v44, v45
	v_cvt_pk_bf16_f32 v43, v46, v47
	v_cvt_pk_bf16_f32 v44, v40, v41
	v_lshl_add_u64 v[40:41], s[66:67], 0, v[50:51]
	v_lshl_add_u64 v[40:41], v[40:41], 0, v[120:121]
	v_add_f32_e32 v32, 1.0, v32
	v_cvt_pk_bf16_f32 v45, v49, v52
	global_store_dwordx4 v[40:41], v[42:45], off
	v_fma_f32 v36, v36, v48, v144
	v_fma_f32 v37, v37, v48, v145
	v_rcp_f32_e32 v42, v32
	v_fma_f32 v32, v33, v48, v141
	v_mul_f32_e32 v32, 0xbfb8aa3b, v32
	v_exp_f32_e32 v32, v32
	v_fma_f32 v38, v38, v48, v142
	v_fma_f32 v39, v39, v48, v143
	v_mul_f32_e32 v36, 0xbfb8aa3b, v36
	v_add_f32_e32 v32, 1.0, v32
	v_rcp_f32_e32 v43, v32
	v_fma_f32 v32, v34, v48, v138
	v_mul_f32_e32 v32, 0xbfb8aa3b, v32
	v_exp_f32_e32 v32, v32
	v_mul_f32_e32 v37, 0xbfb8aa3b, v37
	v_mul_f32_e32 v38, 0xbfb8aa3b, v38
	v_mul_f32_e32 v39, 0xbfb8aa3b, v39
	v_add_f32_e32 v32, 1.0, v32
	v_rcp_f32_e32 v44, v32
	v_fma_f32 v32, v35, v48, v139
	v_mul_f32_e32 v32, 0xbfb8aa3b, v32
	v_exp_f32_e32 v32, v32
	v_exp_f32_e32 v36, v36
	v_exp_f32_e32 v37, v37
	v_exp_f32_e32 v38, v38
	v_exp_f32_e32 v39, v39
	v_add_f32_e32 v32, 1.0, v32
	v_add_f32_e32 v36, 1.0, v36
	v_add_f32_e32 v37, 1.0, v37
	v_add_f32_e32 v38, 1.0, v38
	v_add_f32_e32 v39, 1.0, v39
	v_rcp_f32_e32 v35, v32
	v_rcp_f32_e32 v36, v36
	v_rcp_f32_e32 v37, v37
	v_rcp_f32_e32 v38, v38
	v_rcp_f32_e32 v39, v39
	v_cvt_pk_bf16_f32 v32, v36, v37
	v_cvt_pk_bf16_f32 v33, v38, v39
	v_cvt_pk_bf16_f32 v34, v42, v43
	v_cvt_pk_bf16_f32 v35, v44, v35
	global_store_dwordx4 v[40:41], v[32:35], off offset:256
	s_nop 0
	s_nop 0
	v_add_u32_e32 v34, 0xa0, v156
	v_ashrrev_i32_e32 v35, 31, v34
	v_lshlrev_b64 v[34:35], 11, v[34:35]
	v_fmamk_f32 v32, v194, 0x3a800000, v204
	v_rsq_f32_e32 v32, v32
	s_nop 0
	v_fma_f32 v26, v26, v32, v146
	v_mul_f32_e32 v26, 0xbfb8aa3b, v26
	v_exp_f32_e32 v26, v26
	v_fma_f32 v28, v28, v32, v152
	v_fma_f32 v24, v24, v32, v148
	v_fma_f32 v25, v25, v32, v149
	v_add_f32_e32 v26, 1.0, v26
	v_mul_f32_e32 v28, 0xbfb8aa3b, v28
	v_fma_f32 v29, v29, v32, v153
	v_fma_f32 v30, v30, v32, v150
	v_fma_f32 v31, v31, v32, v151
	v_mul_f32_e32 v24, 0xbfb8aa3b, v24
	v_mul_f32_e32 v25, 0xbfb8aa3b, v25
	v_rcp_f32_e32 v33, v26
	v_fma_f32 v26, v27, v32, v147
	v_exp_f32_e32 v28, v28
	v_mul_f32_e32 v29, 0xbfb8aa3b, v29
	v_mul_f32_e32 v30, 0xbfb8aa3b, v30
	v_mul_f32_e32 v31, 0xbfb8aa3b, v31
	v_exp_f32_e32 v24, v24
	v_exp_f32_e32 v25, v25
	v_mul_f32_e32 v26, 0xbfb8aa3b, v26
	v_exp_f32_e32 v29, v29
	v_exp_f32_e32 v30, v30
	v_exp_f32_e32 v31, v31
	v_exp_f32_e32 v26, v26
	v_fma_f32 v16, v16, v32, v140
	v_mul_f32_e32 v16, 0xbfb8aa3b, v16
	v_exp_f32_e32 v16, v16
	v_add_f32_e32 v28, 1.0, v28
	v_add_f32_e32 v24, 1.0, v24
	v_add_f32_e32 v25, 1.0, v25
	v_rcp_f32_e32 v28, v28
	v_add_f32_e32 v29, 1.0, v29
	v_add_f32_e32 v30, 1.0, v30
	v_add_f32_e32 v31, 1.0, v31
	v_rcp_f32_e32 v24, v24
	v_rcp_f32_e32 v25, v25
	v_add_f32_e32 v26, 1.0, v26
	v_rcp_f32_e32 v29, v29
	v_rcp_f32_e32 v30, v30
	v_rcp_f32_e32 v31, v31
	v_rcp_f32_e32 v36, v26
	v_cvt_pk_bf16_f32 v26, v28, v29
	v_cvt_pk_bf16_f32 v27, v30, v31
	v_cvt_pk_bf16_f32 v28, v24, v25
	v_lshl_add_u64 v[24:25], s[66:67], 0, v[34:35]
	v_lshl_add_u64 v[24:25], v[24:25], 0, v[120:121]
	v_add_f32_e32 v16, 1.0, v16
	v_cvt_pk_bf16_f32 v29, v33, v36
	global_store_dwordx4 v[24:25], v[26:29], off
	v_fma_f32 v20, v20, v32, v144
	v_fma_f32 v21, v21, v32, v145
	v_rcp_f32_e32 v26, v16
	v_fma_f32 v16, v17, v32, v141
	v_mul_f32_e32 v16, 0xbfb8aa3b, v16
	v_exp_f32_e32 v16, v16
	v_fma_f32 v22, v22, v32, v142
	v_fma_f32 v23, v23, v32, v143
	v_mul_f32_e32 v20, 0xbfb8aa3b, v20
	v_add_f32_e32 v16, 1.0, v16
	v_rcp_f32_e32 v27, v16
	v_fma_f32 v16, v18, v32, v138
	v_mul_f32_e32 v16, 0xbfb8aa3b, v16
	v_exp_f32_e32 v16, v16
	v_mul_f32_e32 v21, 0xbfb8aa3b, v21
	v_mul_f32_e32 v22, 0xbfb8aa3b, v22
	v_mul_f32_e32 v23, 0xbfb8aa3b, v23
	v_add_f32_e32 v16, 1.0, v16
	v_rcp_f32_e32 v28, v16
	v_fma_f32 v16, v19, v32, v139
	v_mul_f32_e32 v16, 0xbfb8aa3b, v16
	v_exp_f32_e32 v16, v16
	v_exp_f32_e32 v20, v20
	v_exp_f32_e32 v21, v21
	v_exp_f32_e32 v22, v22
	v_exp_f32_e32 v23, v23
	v_add_f32_e32 v16, 1.0, v16
	v_add_f32_e32 v20, 1.0, v20
	v_add_f32_e32 v21, 1.0, v21
	v_add_f32_e32 v22, 1.0, v22
	v_add_f32_e32 v23, 1.0, v23
	v_rcp_f32_e32 v19, v16
	v_rcp_f32_e32 v20, v20
	v_rcp_f32_e32 v21, v21
	v_rcp_f32_e32 v22, v22
	v_rcp_f32_e32 v23, v23
	v_cvt_pk_bf16_f32 v16, v20, v21
	v_cvt_pk_bf16_f32 v17, v22, v23
	v_cvt_pk_bf16_f32 v18, v26, v27
	v_cvt_pk_bf16_f32 v19, v28, v19
	global_store_dwordx4 v[24:25], v[16:19], off offset:256
	s_nop 0
	s_nop 0
	v_add_u32_e32 v18, 0xb0, v156
	v_ashrrev_i32_e32 v19, 31, v18
	v_lshlrev_b64 v[18:19], 11, v[18:19]
	v_fmamk_f32 v16, v195, 0x3a800000, v204
	v_rsq_f32_e32 v16, v16
	s_nop 0
	v_fma_f32 v10, v10, v16, v146
	v_mul_f32_e32 v10, 0xbfb8aa3b, v10
	v_exp_f32_e32 v10, v10
	v_fma_f32 v12, v12, v16, v152
	v_fma_f32 v8, v8, v16, v148
	v_fmac_f32_e32 v149, v9, v16
	v_mul_f32_e32 v12, 0xbfb8aa3b, v12
	v_fmac_f32_e32 v153, v13, v16
	v_fma_f32 v14, v14, v16, v150
	v_fmac_f32_e32 v151, v15, v16
	v_mul_f32_e32 v8, 0xbfb8aa3b, v8
	v_mul_f32_e32 v9, 0xbfb8aa3b, v149
	v_add_f32_e32 v10, 1.0, v10
	v_fmac_f32_e32 v147, v11, v16
	v_exp_f32_e32 v12, v12
	v_mul_f32_e32 v13, 0xbfb8aa3b, v153
	v_mul_f32_e32 v14, 0xbfb8aa3b, v14
	v_mul_f32_e32 v15, 0xbfb8aa3b, v151
	v_exp_f32_e32 v8, v8
	v_exp_f32_e32 v9, v9
	v_rcp_f32_e32 v17, v10
	v_mul_f32_e32 v10, 0xbfb8aa3b, v147
	v_exp_f32_e32 v13, v13
	v_exp_f32_e32 v14, v14
	v_exp_f32_e32 v15, v15
	v_exp_f32_e32 v10, v10
	v_fma_f32 v0, v0, v16, v140
	v_mul_f32_e32 v0, 0xbfb8aa3b, v0
	v_exp_f32_e32 v0, v0
	v_add_f32_e32 v12, 1.0, v12
	v_add_f32_e32 v8, 1.0, v8
	v_add_f32_e32 v9, 1.0, v9
	v_rcp_f32_e32 v12, v12
	v_add_f32_e32 v13, 1.0, v13
	v_add_f32_e32 v14, 1.0, v14
	v_add_f32_e32 v15, 1.0, v15
	v_rcp_f32_e32 v8, v8
	v_rcp_f32_e32 v9, v9
	v_add_f32_e32 v10, 1.0, v10
	v_rcp_f32_e32 v13, v13
	v_rcp_f32_e32 v14, v14
	v_rcp_f32_e32 v15, v15
	v_rcp_f32_e32 v20, v10
	v_cvt_pk_bf16_f32 v10, v12, v13
	v_cvt_pk_bf16_f32 v11, v14, v15
	v_cvt_pk_bf16_f32 v12, v8, v9
	v_lshl_add_u64 v[8:9], s[66:67], 0, v[18:19]
	v_lshl_add_u64 v[8:9], v[8:9], 0, v[120:121]
	v_add_f32_e32 v0, 1.0, v0
	v_fmac_f32_e32 v141, v1, v16
	v_cvt_pk_bf16_f32 v13, v17, v20
	global_store_dwordx4 v[8:9], v[10:13], off
	v_fmac_f32_e32 v139, v3, v16
	v_fma_f32 v4, v4, v16, v144
	v_rcp_f32_e32 v10, v0
	v_mul_f32_e32 v0, 0xbfb8aa3b, v141
	v_exp_f32_e32 v0, v0
	v_fmac_f32_e32 v145, v5, v16
	v_fma_f32 v6, v6, v16, v142
	v_fmac_f32_e32 v143, v7, v16
	v_add_f32_e32 v0, 1.0, v0
	v_rcp_f32_e32 v11, v0
	v_fma_f32 v0, v2, v16, v138
	v_mul_f32_e32 v0, 0xbfb8aa3b, v0
	v_exp_f32_e32 v0, v0
	v_mul_f32_e32 v4, 0xbfb8aa3b, v4
	v_mul_f32_e32 v5, 0xbfb8aa3b, v145
	v_mul_f32_e32 v6, 0xbfb8aa3b, v6
	v_add_f32_e32 v0, 1.0, v0
	v_rcp_f32_e32 v12, v0
	v_mul_f32_e32 v0, 0xbfb8aa3b, v139
	v_mul_f32_e32 v7, 0xbfb8aa3b, v143
	v_exp_f32_e32 v0, v0
	v_exp_f32_e32 v4, v4
	v_exp_f32_e32 v5, v5
	v_exp_f32_e32 v6, v6
	v_exp_f32_e32 v7, v7
	v_add_f32_e32 v0, 1.0, v0
	v_add_f32_e32 v4, 1.0, v4
	v_add_f32_e32 v5, 1.0, v5
	v_add_f32_e32 v6, 1.0, v6
	v_add_f32_e32 v7, 1.0, v7
	v_rcp_f32_e32 v3, v0
	v_rcp_f32_e32 v4, v4
	v_rcp_f32_e32 v5, v5
	v_rcp_f32_e32 v6, v6
	v_rcp_f32_e32 v7, v7
	v_cvt_pk_bf16_f32 v0, v4, v5
	v_cvt_pk_bf16_f32 v1, v6, v7
	v_cvt_pk_bf16_f32 v2, v10, v11
	v_cvt_pk_bf16_f32 v3, v12, v3
	global_store_dwordx4 v[8:9], v[0:3], off offset:256
	s_cbranch_vccnz .LBB0_471
	s_andn2_b64 vcc, exec, s[6:7]
	s_cbranch_vccnz .LBB0_470
	s_barrier
	s_branch .LBB0_470

.LBB0_520:
	s_ashr_i32 s11, s2, 4
	v_lshl_or_b32 v158, s3, 8, v168
	s_mul_hi_i32 s3, s11, 0x7400
	s_mulk_i32 s11, 0x7400
	s_add_u32 s18, s31, s11
	v_ashrrev_i32_e32 v159, 31, v158
	s_addc_u32 s19, s34, s3
	v_lshlrev_b64 v[138:139], 2, v[158:159]
	v_lshl_add_u64 v[162:163], s[18:19], 0, v[138:139]
	v_lshl_add_u64 v[174:175], s[0:1], 0, v[138:139]
	global_load_dwordx4 v[138:141], v[162:163], off offset:16
	global_load_dwordx4 v[142:145], v[162:163], off
	global_load_dwordx4 v[154:157], v[174:175], off offset:16
	global_load_dwordx4 v[146:149], v[174:175], off
	global_load_dwordx4 v[178:181], v[162:163], off offset:528
	global_load_dwordx4 v[182:185], v[162:163], off offset:512
	global_load_dwordx4 v[170:173], v[174:175], off offset:528
	v_lshl_add_u32 v186, s2, 8, v166
	v_ashrrev_i32_e32 v187, 31, v186
	v_lshl_add_u64 v[186:187], v[186:187], 2, s[42:43]
	global_load_dword v188, v[186:187], off
	global_load_dword v189, v[186:187], off offset:64
	global_load_dword v190, v[186:187], off offset:128
	global_load_dword v191, v[186:187], off offset:192
	global_load_dword v192, v[186:187], off offset:512
	global_load_dword v193, v[186:187], off offset:576
	global_load_dword v194, v[186:187], off offset:640
	global_load_dword v195, v[186:187], off offset:704
	global_load_dwordx4 v[174:177], v[174:175], off offset:512
	s_mov_b64 s[18:19], -1
	s_andn2_b64 vcc, exec, s[4:5]
	s_waitcnt vmcnt(0)
	v_pk_add_f32 v[150:151], v[144:145], v[148:149]
	v_pk_add_f32 v[152:153], v[142:143], v[146:147]
	v_pk_add_f32 v[146:147], v[140:141], v[156:157]
	v_pk_add_f32 v[148:149], v[138:139], v[154:155]
	v_pk_add_f32 v[144:145], v[182:183], v[174:175]
	v_pk_add_f32 v[138:139], v[180:181], v[172:173]
	v_lshl_add_u32 v156, s2, 8, v166
	v_ashrrev_i32_e32 v157, 31, v156
	v_pk_add_f32 v[142:143], v[184:185], v[176:177]
	v_pk_add_f32 v[140:141], v[178:179], v[170:171]
	v_lshl_add_u64 v[154:155], v[156:157], 2, s[42:43]
	v_fmamk_f32 v162, v188, 0x3a800000, v204
	v_rsq_f32_e32 v170, v162
	v_lshlrev_b64 v[162:163], 11, v[156:157]
	v_fma_f32 v124, v124, v170, v152
	v_fma_f32 v125, v125, v170, v153
	v_fma_f32 v126, v126, v170, v150
	v_fma_f32 v127, v127, v170, v151
	v_fma_f32 v120, v120, v170, v148
	v_fma_f32 v121, v121, v170, v149
	v_fma_f32 v122, v122, v170, v146
	v_fma_f32 v123, v123, v170, v147
	v_mul_f32_e32 v124, 0xbfb8aa3b, v124
	v_mul_f32_e32 v125, 0xbfb8aa3b, v125
	v_mul_f32_e32 v126, 0xbfb8aa3b, v126
	v_mul_f32_e32 v127, 0xbfb8aa3b, v127
	v_mul_f32_e32 v120, 0xbfb8aa3b, v120
	v_mul_f32_e32 v121, 0xbfb8aa3b, v121
	v_mul_f32_e32 v122, 0xbfb8aa3b, v122
	v_mul_f32_e32 v123, 0xbfb8aa3b, v123
	v_exp_f32_e32 v124, v124
	v_exp_f32_e32 v125, v125
	v_exp_f32_e32 v126, v126
	v_exp_f32_e32 v127, v127
	v_exp_f32_e32 v120, v120
	v_exp_f32_e32 v121, v121
	v_exp_f32_e32 v122, v122
	v_exp_f32_e32 v123, v123
	v_fma_f32 v112, v112, v170, v140
	v_mul_f32_e32 v112, 0xbfb8aa3b, v112
	v_exp_f32_e32 v112, v112
	v_add_f32_e32 v124, 1.0, v124
	v_add_f32_e32 v125, 1.0, v125
	v_add_f32_e32 v126, 1.0, v126
	v_add_f32_e32 v127, 1.0, v127
	v_add_f32_e32 v120, 1.0, v120
	v_add_f32_e32 v121, 1.0, v121
	v_add_f32_e32 v122, 1.0, v122
	v_add_f32_e32 v123, 1.0, v123
	v_rcp_f32_e32 v124, v124
	v_rcp_f32_e32 v125, v125
	v_rcp_f32_e32 v126, v126
	v_rcp_f32_e32 v127, v127
	v_rcp_f32_e32 v120, v120
	v_rcp_f32_e32 v121, v121
	v_rcp_f32_e32 v122, v122
	v_rcp_f32_e32 v123, v123
	v_cvt_pk_bf16_f32 v124, v124, v125
	v_cvt_pk_bf16_f32 v125, v126, v127
	v_cvt_pk_bf16_f32 v126, v120, v121
	v_cvt_pk_bf16_f32 v127, v122, v123
	v_lshl_add_u64 v[122:123], s[70:71], 0, v[162:163]
	v_lshlrev_b64 v[120:121], 1, v[158:159]
	v_lshl_add_u64 v[122:123], v[122:123], 0, v[120:121]
	v_add_f32_e32 v112, 1.0, v112
	global_store_dwordx4 v[122:123], v[124:127], off
	v_fma_f32 v116, v116, v170, v144
	v_fma_f32 v117, v117, v170, v145
	v_rcp_f32_e32 v124, v112
	v_fma_f32 v112, v113, v170, v141
	v_mul_f32_e32 v112, 0xbfb8aa3b, v112
	v_exp_f32_e32 v112, v112
	v_fma_f32 v118, v118, v170, v142
	v_fma_f32 v119, v119, v170, v143
	v_mul_f32_e32 v116, 0xbfb8aa3b, v116
	v_add_f32_e32 v112, 1.0, v112
	v_rcp_f32_e32 v125, v112
	v_fma_f32 v112, v114, v170, v138
	v_mul_f32_e32 v112, 0xbfb8aa3b, v112
	v_exp_f32_e32 v112, v112
	v_mul_f32_e32 v117, 0xbfb8aa3b, v117
	v_mul_f32_e32 v118, 0xbfb8aa3b, v118
	v_mul_f32_e32 v119, 0xbfb8aa3b, v119
	v_add_f32_e32 v112, 1.0, v112
	v_rcp_f32_e32 v126, v112
	v_fma_f32 v112, v115, v170, v139
	v_mul_f32_e32 v112, 0xbfb8aa3b, v112
	v_exp_f32_e32 v112, v112
	v_exp_f32_e32 v116, v116
	v_exp_f32_e32 v117, v117
	v_exp_f32_e32 v118, v118
	v_exp_f32_e32 v119, v119
	v_add_f32_e32 v112, 1.0, v112
	v_add_f32_e32 v116, 1.0, v116
	v_add_f32_e32 v117, 1.0, v117
	v_add_f32_e32 v118, 1.0, v118
	v_add_f32_e32 v119, 1.0, v119
	v_rcp_f32_e32 v115, v112
	v_rcp_f32_e32 v116, v116
	v_rcp_f32_e32 v117, v117
	v_rcp_f32_e32 v118, v118
	v_rcp_f32_e32 v119, v119
	v_cvt_pk_bf16_f32 v112, v116, v117
	v_cvt_pk_bf16_f32 v113, v118, v119
	v_cvt_pk_bf16_f32 v114, v124, v125
	v_cvt_pk_bf16_f32 v115, v126, v115
	global_store_dwordx4 v[122:123], v[112:115], off offset:256
	s_nop 0
	s_nop 0
	v_or_b32_e32 v114, 16, v156
	v_ashrrev_i32_e32 v115, 31, v114
	v_lshlrev_b64 v[114:115], 11, v[114:115]
	v_fmamk_f32 v112, v189, 0x3a800000, v204
	v_rsq_f32_e32 v112, v112
	s_nop 0
	v_fma_f32 v106, v106, v112, v146
	v_mul_f32_e32 v106, 0xbfb8aa3b, v106
	v_exp_f32_e32 v106, v106
	v_fma_f32 v108, v108, v112, v152
	v_fma_f32 v104, v104, v112, v148
	v_fma_f32 v105, v105, v112, v149
	v_add_f32_e32 v106, 1.0, v106
	v_mul_f32_e32 v108, 0xbfb8aa3b, v108
	v_fma_f32 v109, v109, v112, v153
	v_fma_f32 v110, v110, v112, v150
	v_fma_f32 v111, v111, v112, v151
	v_mul_f32_e32 v104, 0xbfb8aa3b, v104
	v_mul_f32_e32 v105, 0xbfb8aa3b, v105
	v_rcp_f32_e32 v113, v106
	v_fma_f32 v106, v107, v112, v147
	v_exp_f32_e32 v108, v108
	v_mul_f32_e32 v109, 0xbfb8aa3b, v109
	v_mul_f32_e32 v110, 0xbfb8aa3b, v110
	v_mul_f32_e32 v111, 0xbfb8aa3b, v111
	v_exp_f32_e32 v104, v104
	v_exp_f32_e32 v105, v105
	v_mul_f32_e32 v106, 0xbfb8aa3b, v106
	v_exp_f32_e32 v109, v109
	v_exp_f32_e32 v110, v110
	v_exp_f32_e32 v111, v111
	v_exp_f32_e32 v106, v106
	v_fma_f32 v96, v96, v112, v140
	v_mul_f32_e32 v96, 0xbfb8aa3b, v96
	v_exp_f32_e32 v96, v96
	v_add_f32_e32 v108, 1.0, v108
	v_add_f32_e32 v104, 1.0, v104
	v_add_f32_e32 v105, 1.0, v105
	v_rcp_f32_e32 v108, v108
	v_add_f32_e32 v109, 1.0, v109
	v_add_f32_e32 v110, 1.0, v110
	v_add_f32_e32 v111, 1.0, v111
	v_rcp_f32_e32 v104, v104
	v_rcp_f32_e32 v105, v105
	v_add_f32_e32 v106, 1.0, v106
	v_rcp_f32_e32 v109, v109
	v_rcp_f32_e32 v110, v110
	v_rcp_f32_e32 v111, v111
	v_rcp_f32_e32 v116, v106
	v_cvt_pk_bf16_f32 v106, v108, v109
	v_cvt_pk_bf16_f32 v107, v110, v111
	v_cvt_pk_bf16_f32 v108, v104, v105
	v_lshl_add_u64 v[104:105], s[70:71], 0, v[114:115]
	v_lshl_add_u64 v[104:105], v[104:105], 0, v[120:121]
	v_add_f32_e32 v96, 1.0, v96
	v_cvt_pk_bf16_f32 v109, v113, v116
	global_store_dwordx4 v[104:105], v[106:109], off
	v_fma_f32 v100, v100, v112, v144
	v_fma_f32 v101, v101, v112, v145
	v_rcp_f32_e32 v106, v96
	v_fma_f32 v96, v97, v112, v141
	v_mul_f32_e32 v96, 0xbfb8aa3b, v96
	v_exp_f32_e32 v96, v96
	v_fma_f32 v102, v102, v112, v142
	v_fma_f32 v103, v103, v112, v143
	v_mul_f32_e32 v100, 0xbfb8aa3b, v100
	v_add_f32_e32 v96, 1.0, v96
	v_rcp_f32_e32 v107, v96
	v_fma_f32 v96, v98, v112, v138
	v_mul_f32_e32 v96, 0xbfb8aa3b, v96
	v_exp_f32_e32 v96, v96
	v_mul_f32_e32 v101, 0xbfb8aa3b, v101
	v_mul_f32_e32 v102, 0xbfb8aa3b, v102
	v_mul_f32_e32 v103, 0xbfb8aa3b, v103
	v_add_f32_e32 v96, 1.0, v96
	v_rcp_f32_e32 v108, v96
	v_fma_f32 v96, v99, v112, v139
	v_mul_f32_e32 v96, 0xbfb8aa3b, v96
	v_exp_f32_e32 v96, v96
	v_exp_f32_e32 v100, v100
	v_exp_f32_e32 v101, v101
	v_exp_f32_e32 v102, v102
	v_exp_f32_e32 v103, v103
	v_add_f32_e32 v96, 1.0, v96
	v_add_f32_e32 v100, 1.0, v100
	v_add_f32_e32 v101, 1.0, v101
	v_add_f32_e32 v102, 1.0, v102
	v_add_f32_e32 v103, 1.0, v103
	v_rcp_f32_e32 v99, v96
	v_rcp_f32_e32 v100, v100
	v_rcp_f32_e32 v101, v101
	v_rcp_f32_e32 v102, v102
	v_rcp_f32_e32 v103, v103
	v_cvt_pk_bf16_f32 v96, v100, v101
	v_cvt_pk_bf16_f32 v97, v102, v103
	v_cvt_pk_bf16_f32 v98, v106, v107
	v_cvt_pk_bf16_f32 v99, v108, v99
	global_store_dwordx4 v[104:105], v[96:99], off offset:256
	s_nop 0
	s_nop 0
	v_or_b32_e32 v98, 32, v156
	v_ashrrev_i32_e32 v99, 31, v98
	v_lshlrev_b64 v[98:99], 11, v[98:99]
	v_fmamk_f32 v96, v190, 0x3a800000, v204
	v_rsq_f32_e32 v96, v96
	s_nop 0
	v_fma_f32 v90, v90, v96, v146
	v_mul_f32_e32 v90, 0xbfb8aa3b, v90
	v_exp_f32_e32 v90, v90
	v_fma_f32 v92, v92, v96, v152
	v_fma_f32 v88, v88, v96, v148
	v_fma_f32 v89, v89, v96, v149
	v_add_f32_e32 v90, 1.0, v90
	v_mul_f32_e32 v92, 0xbfb8aa3b, v92
	v_fma_f32 v93, v93, v96, v153
	v_fma_f32 v94, v94, v96, v150
	v_fma_f32 v95, v95, v96, v151
	v_mul_f32_e32 v88, 0xbfb8aa3b, v88
	v_mul_f32_e32 v89, 0xbfb8aa3b, v89
	v_rcp_f32_e32 v97, v90
	v_fma_f32 v90, v91, v96, v147
	v_exp_f32_e32 v92, v92
	v_mul_f32_e32 v93, 0xbfb8aa3b, v93
	v_mul_f32_e32 v94, 0xbfb8aa3b, v94
	v_mul_f32_e32 v95, 0xbfb8aa3b, v95
	v_exp_f32_e32 v88, v88
	v_exp_f32_e32 v89, v89
	v_mul_f32_e32 v90, 0xbfb8aa3b, v90
	v_exp_f32_e32 v93, v93
	v_exp_f32_e32 v94, v94
	v_exp_f32_e32 v95, v95
	v_exp_f32_e32 v90, v90
	v_fma_f32 v80, v80, v96, v140
	v_mul_f32_e32 v80, 0xbfb8aa3b, v80
	v_exp_f32_e32 v80, v80
	v_add_f32_e32 v92, 1.0, v92
	v_add_f32_e32 v88, 1.0, v88
	v_add_f32_e32 v89, 1.0, v89
	v_rcp_f32_e32 v92, v92
	v_add_f32_e32 v93, 1.0, v93
	v_add_f32_e32 v94, 1.0, v94
	v_add_f32_e32 v95, 1.0, v95
	v_rcp_f32_e32 v88, v88
	v_rcp_f32_e32 v89, v89
	v_add_f32_e32 v90, 1.0, v90
	v_rcp_f32_e32 v93, v93
	v_rcp_f32_e32 v94, v94
	v_rcp_f32_e32 v95, v95
	v_rcp_f32_e32 v100, v90
	v_cvt_pk_bf16_f32 v90, v92, v93
	v_cvt_pk_bf16_f32 v91, v94, v95
	v_cvt_pk_bf16_f32 v92, v88, v89
	v_lshl_add_u64 v[88:89], s[70:71], 0, v[98:99]
	v_lshl_add_u64 v[88:89], v[88:89], 0, v[120:121]
	v_add_f32_e32 v80, 1.0, v80
	v_cvt_pk_bf16_f32 v93, v97, v100
	global_store_dwordx4 v[88:89], v[90:93], off
	v_fma_f32 v84, v84, v96, v144
	v_fma_f32 v85, v85, v96, v145
	v_rcp_f32_e32 v90, v80
	v_fma_f32 v80, v81, v96, v141
	v_mul_f32_e32 v80, 0xbfb8aa3b, v80
	v_exp_f32_e32 v80, v80
	v_fma_f32 v86, v86, v96, v142
	v_fma_f32 v87, v87, v96, v143
	v_mul_f32_e32 v84, 0xbfb8aa3b, v84
	v_add_f32_e32 v80, 1.0, v80
	v_rcp_f32_e32 v91, v80
	v_fma_f32 v80, v82, v96, v138
	v_mul_f32_e32 v80, 0xbfb8aa3b, v80
	v_exp_f32_e32 v80, v80
	v_mul_f32_e32 v85, 0xbfb8aa3b, v85
	v_mul_f32_e32 v86, 0xbfb8aa3b, v86
	v_mul_f32_e32 v87, 0xbfb8aa3b, v87
	v_add_f32_e32 v80, 1.0, v80
	v_rcp_f32_e32 v92, v80
	v_fma_f32 v80, v83, v96, v139
	v_mul_f32_e32 v80, 0xbfb8aa3b, v80
	v_exp_f32_e32 v80, v80
	v_exp_f32_e32 v84, v84
	v_exp_f32_e32 v85, v85
	v_exp_f32_e32 v86, v86
	v_exp_f32_e32 v87, v87
	v_add_f32_e32 v80, 1.0, v80
	v_add_f32_e32 v84, 1.0, v84
	v_add_f32_e32 v85, 1.0, v85
	v_add_f32_e32 v86, 1.0, v86
	v_add_f32_e32 v87, 1.0, v87
	v_rcp_f32_e32 v83, v80
	v_rcp_f32_e32 v84, v84
	v_rcp_f32_e32 v85, v85
	v_rcp_f32_e32 v86, v86
	v_rcp_f32_e32 v87, v87
	v_cvt_pk_bf16_f32 v80, v84, v85
	v_cvt_pk_bf16_f32 v81, v86, v87
	v_cvt_pk_bf16_f32 v82, v90, v91
	v_cvt_pk_bf16_f32 v83, v92, v83
	global_store_dwordx4 v[88:89], v[80:83], off offset:256
	s_nop 0
	s_nop 0
	v_or_b32_e32 v82, 48, v156
	v_ashrrev_i32_e32 v83, 31, v82
	v_lshlrev_b64 v[82:83], 11, v[82:83]
	v_fmamk_f32 v80, v191, 0x3a800000, v204
	v_rsq_f32_e32 v80, v80
	s_nop 0
	v_fma_f32 v74, v74, v80, v146
	v_mul_f32_e32 v74, 0xbfb8aa3b, v74
	v_exp_f32_e32 v74, v74
	v_fma_f32 v76, v76, v80, v152
	v_fma_f32 v72, v72, v80, v148
	v_fma_f32 v73, v73, v80, v149
	v_add_f32_e32 v74, 1.0, v74
	v_mul_f32_e32 v76, 0xbfb8aa3b, v76
	v_fma_f32 v77, v77, v80, v153
	v_fma_f32 v78, v78, v80, v150
	v_fma_f32 v79, v79, v80, v151
	v_mul_f32_e32 v72, 0xbfb8aa3b, v72
	v_mul_f32_e32 v73, 0xbfb8aa3b, v73
	v_rcp_f32_e32 v81, v74
	v_fma_f32 v74, v75, v80, v147
	v_exp_f32_e32 v76, v76
	v_mul_f32_e32 v77, 0xbfb8aa3b, v77
	v_mul_f32_e32 v78, 0xbfb8aa3b, v78
	v_mul_f32_e32 v79, 0xbfb8aa3b, v79
	v_exp_f32_e32 v72, v72
	v_exp_f32_e32 v73, v73
	v_mul_f32_e32 v74, 0xbfb8aa3b, v74
	v_exp_f32_e32 v77, v77
	v_exp_f32_e32 v78, v78
	v_exp_f32_e32 v79, v79
	v_exp_f32_e32 v74, v74
	v_fma_f32 v64, v64, v80, v140
	v_mul_f32_e32 v64, 0xbfb8aa3b, v64
	v_exp_f32_e32 v64, v64
	v_add_f32_e32 v76, 1.0, v76
	v_add_f32_e32 v72, 1.0, v72
	v_add_f32_e32 v73, 1.0, v73
	v_rcp_f32_e32 v76, v76
	v_add_f32_e32 v77, 1.0, v77
	v_add_f32_e32 v78, 1.0, v78
	v_add_f32_e32 v79, 1.0, v79
	v_rcp_f32_e32 v72, v72
	v_rcp_f32_e32 v73, v73
	v_add_f32_e32 v74, 1.0, v74
	v_rcp_f32_e32 v77, v77
	v_rcp_f32_e32 v78, v78
	v_rcp_f32_e32 v79, v79
	v_rcp_f32_e32 v84, v74
	v_cvt_pk_bf16_f32 v74, v76, v77
	v_cvt_pk_bf16_f32 v75, v78, v79
	v_cvt_pk_bf16_f32 v76, v72, v73
	v_lshl_add_u64 v[72:73], s[70:71], 0, v[82:83]
	v_lshl_add_u64 v[72:73], v[72:73], 0, v[120:121]
	v_add_f32_e32 v64, 1.0, v64
	v_cvt_pk_bf16_f32 v77, v81, v84
	global_store_dwordx4 v[72:73], v[74:77], off
	v_fma_f32 v68, v68, v80, v144
	v_fma_f32 v69, v69, v80, v145
	v_rcp_f32_e32 v74, v64
	v_fma_f32 v64, v65, v80, v141
	v_mul_f32_e32 v64, 0xbfb8aa3b, v64
	v_exp_f32_e32 v64, v64
	v_fma_f32 v70, v70, v80, v142
	v_fma_f32 v71, v71, v80, v143
	v_mul_f32_e32 v68, 0xbfb8aa3b, v68
	v_add_f32_e32 v64, 1.0, v64
	v_rcp_f32_e32 v75, v64
	v_fma_f32 v64, v66, v80, v138
	v_mul_f32_e32 v64, 0xbfb8aa3b, v64
	v_exp_f32_e32 v64, v64
	v_mul_f32_e32 v69, 0xbfb8aa3b, v69
	v_mul_f32_e32 v70, 0xbfb8aa3b, v70
	v_mul_f32_e32 v71, 0xbfb8aa3b, v71
	v_add_f32_e32 v64, 1.0, v64
	v_rcp_f32_e32 v76, v64
	v_fma_f32 v64, v67, v80, v139
	v_mul_f32_e32 v64, 0xbfb8aa3b, v64
	v_exp_f32_e32 v64, v64
	v_exp_f32_e32 v68, v68
	v_exp_f32_e32 v69, v69
	v_exp_f32_e32 v70, v70
	v_exp_f32_e32 v71, v71
	v_add_f32_e32 v64, 1.0, v64
	v_add_f32_e32 v68, 1.0, v68
	v_add_f32_e32 v69, 1.0, v69
	v_add_f32_e32 v70, 1.0, v70
	v_add_f32_e32 v71, 1.0, v71
	v_rcp_f32_e32 v67, v64
	v_rcp_f32_e32 v68, v68
	v_rcp_f32_e32 v69, v69
	v_rcp_f32_e32 v70, v70
	v_rcp_f32_e32 v71, v71
	v_cvt_pk_bf16_f32 v64, v68, v69
	v_cvt_pk_bf16_f32 v65, v70, v71
	v_cvt_pk_bf16_f32 v66, v74, v75
	v_cvt_pk_bf16_f32 v67, v76, v67
	global_store_dwordx4 v[72:73], v[64:67], off offset:256
	s_nop 0
	s_nop 0
	v_add_u32_e32 v66, 0x80, v156
	v_ashrrev_i32_e32 v67, 31, v66
	v_lshlrev_b64 v[66:67], 11, v[66:67]
	v_fmamk_f32 v64, v192, 0x3a800000, v204
	v_rsq_f32_e32 v64, v64
	s_nop 0
	v_fma_f32 v58, v58, v64, v146
	v_mul_f32_e32 v58, 0xbfb8aa3b, v58
	v_exp_f32_e32 v58, v58
	v_fma_f32 v60, v60, v64, v152
	v_fma_f32 v56, v56, v64, v148
	v_fma_f32 v57, v57, v64, v149
	v_add_f32_e32 v58, 1.0, v58
	v_mul_f32_e32 v60, 0xbfb8aa3b, v60
	v_fma_f32 v61, v61, v64, v153
	v_fma_f32 v62, v62, v64, v150
	v_fma_f32 v63, v63, v64, v151
	v_mul_f32_e32 v56, 0xbfb8aa3b, v56
	v_mul_f32_e32 v57, 0xbfb8aa3b, v57
	v_rcp_f32_e32 v65, v58
	v_fma_f32 v58, v59, v64, v147
	v_exp_f32_e32 v60, v60
	v_mul_f32_e32 v61, 0xbfb8aa3b, v61
	v_mul_f32_e32 v62, 0xbfb8aa3b, v62
	v_mul_f32_e32 v63, 0xbfb8aa3b, v63
	v_exp_f32_e32 v56, v56
	v_exp_f32_e32 v57, v57
	v_mul_f32_e32 v58, 0xbfb8aa3b, v58
	v_exp_f32_e32 v61, v61
	v_exp_f32_e32 v62, v62
	v_exp_f32_e32 v63, v63
	v_exp_f32_e32 v58, v58
	v_fma_f32 v48, v48, v64, v140
	v_mul_f32_e32 v48, 0xbfb8aa3b, v48
	v_exp_f32_e32 v48, v48
	v_add_f32_e32 v60, 1.0, v60
	v_add_f32_e32 v56, 1.0, v56
	v_add_f32_e32 v57, 1.0, v57
	v_rcp_f32_e32 v60, v60
	v_add_f32_e32 v61, 1.0, v61
	v_add_f32_e32 v62, 1.0, v62
	v_add_f32_e32 v63, 1.0, v63
	v_rcp_f32_e32 v56, v56
	v_rcp_f32_e32 v57, v57
	v_add_f32_e32 v58, 1.0, v58
	v_rcp_f32_e32 v61, v61
	v_rcp_f32_e32 v62, v62
	v_rcp_f32_e32 v63, v63
	v_rcp_f32_e32 v68, v58
	v_cvt_pk_bf16_f32 v58, v60, v61
	v_cvt_pk_bf16_f32 v59, v62, v63
	v_cvt_pk_bf16_f32 v60, v56, v57
	v_lshl_add_u64 v[56:57], s[70:71], 0, v[66:67]
	v_lshl_add_u64 v[56:57], v[56:57], 0, v[120:121]
	v_add_f32_e32 v48, 1.0, v48
	v_cvt_pk_bf16_f32 v61, v65, v68
	global_store_dwordx4 v[56:57], v[58:61], off
	v_fma_f32 v52, v52, v64, v144
	v_fma_f32 v53, v53, v64, v145
	v_rcp_f32_e32 v58, v48
	v_fma_f32 v48, v49, v64, v141
	v_mul_f32_e32 v48, 0xbfb8aa3b, v48
	v_exp_f32_e32 v48, v48
	v_fma_f32 v54, v54, v64, v142
	v_fma_f32 v55, v55, v64, v143
	v_mul_f32_e32 v52, 0xbfb8aa3b, v52
	v_add_f32_e32 v48, 1.0, v48
	v_rcp_f32_e32 v59, v48
	v_fma_f32 v48, v50, v64, v138
	v_mul_f32_e32 v48, 0xbfb8aa3b, v48
	v_exp_f32_e32 v48, v48
	v_mul_f32_e32 v53, 0xbfb8aa3b, v53
	v_mul_f32_e32 v54, 0xbfb8aa3b, v54
	v_mul_f32_e32 v55, 0xbfb8aa3b, v55
	v_add_f32_e32 v48, 1.0, v48
	v_rcp_f32_e32 v60, v48
	v_fma_f32 v48, v51, v64, v139
	v_mul_f32_e32 v48, 0xbfb8aa3b, v48
	v_exp_f32_e32 v48, v48
	v_exp_f32_e32 v52, v52
	v_exp_f32_e32 v53, v53
	v_exp_f32_e32 v54, v54
	v_exp_f32_e32 v55, v55
	v_add_f32_e32 v48, 1.0, v48
	v_add_f32_e32 v52, 1.0, v52
	v_add_f32_e32 v53, 1.0, v53
	v_add_f32_e32 v54, 1.0, v54
	v_add_f32_e32 v55, 1.0, v55
	v_rcp_f32_e32 v51, v48
	v_rcp_f32_e32 v52, v52
	v_rcp_f32_e32 v53, v53
	v_rcp_f32_e32 v54, v54
	v_rcp_f32_e32 v55, v55
	v_cvt_pk_bf16_f32 v48, v52, v53
	v_cvt_pk_bf16_f32 v49, v54, v55
	v_cvt_pk_bf16_f32 v50, v58, v59
	v_cvt_pk_bf16_f32 v51, v60, v51
	global_store_dwordx4 v[56:57], v[48:51], off offset:256
	s_nop 0
	s_nop 0
	v_add_u32_e32 v50, 0x90, v156
	v_ashrrev_i32_e32 v51, 31, v50
	v_lshlrev_b64 v[50:51], 11, v[50:51]
	v_fmamk_f32 v48, v193, 0x3a800000, v204
	v_rsq_f32_e32 v48, v48
	s_nop 0
	v_fma_f32 v42, v42, v48, v146
	v_mul_f32_e32 v42, 0xbfb8aa3b, v42
	v_exp_f32_e32 v42, v42
	v_fma_f32 v44, v44, v48, v152
	v_fma_f32 v40, v40, v48, v148
	v_fma_f32 v41, v41, v48, v149
	v_add_f32_e32 v42, 1.0, v42
	v_mul_f32_e32 v44, 0xbfb8aa3b, v44
	v_fma_f32 v45, v45, v48, v153
	v_fma_f32 v46, v46, v48, v150
	v_fma_f32 v47, v47, v48, v151
	v_mul_f32_e32 v40, 0xbfb8aa3b, v40
	v_mul_f32_e32 v41, 0xbfb8aa3b, v41
	v_rcp_f32_e32 v49, v42
	v_fma_f32 v42, v43, v48, v147
	v_exp_f32_e32 v44, v44
	v_mul_f32_e32 v45, 0xbfb8aa3b, v45
	v_mul_f32_e32 v46, 0xbfb8aa3b, v46
	v_mul_f32_e32 v47, 0xbfb8aa3b, v47
	v_exp_f32_e32 v40, v40
	v_exp_f32_e32 v41, v41
	v_mul_f32_e32 v42, 0xbfb8aa3b, v42
	v_exp_f32_e32 v45, v45
	v_exp_f32_e32 v46, v46
	v_exp_f32_e32 v47, v47
	v_exp_f32_e32 v42, v42
	v_fma_f32 v32, v32, v48, v140
	v_mul_f32_e32 v32, 0xbfb8aa3b, v32
	v_exp_f32_e32 v32, v32
	v_add_f32_e32 v44, 1.0, v44
	v_add_f32_e32 v40, 1.0, v40
	v_add_f32_e32 v41, 1.0, v41
	v_rcp_f32_e32 v44, v44
	v_add_f32_e32 v45, 1.0, v45
	v_add_f32_e32 v46, 1.0, v46
	v_add_f32_e32 v47, 1.0, v47
	v_rcp_f32_e32 v40, v40
	v_rcp_f32_e32 v41, v41
	v_add_f32_e32 v42, 1.0, v42
	v_rcp_f32_e32 v45, v45
	v_rcp_f32_e32 v46, v46
	v_rcp_f32_e32 v47, v47
	v_rcp_f32_e32 v52, v42
	v_cvt_pk_bf16_f32 v42, v44, v45
	v_cvt_pk_bf16_f32 v43, v46, v47
	v_cvt_pk_bf16_f32 v44, v40, v41
	v_lshl_add_u64 v[40:41], s[70:71], 0, v[50:51]
	v_lshl_add_u64 v[40:41], v[40:41], 0, v[120:121]
	v_add_f32_e32 v32, 1.0, v32
	v_cvt_pk_bf16_f32 v45, v49, v52
	global_store_dwordx4 v[40:41], v[42:45], off
	v_fma_f32 v36, v36, v48, v144
	v_fma_f32 v37, v37, v48, v145
	v_rcp_f32_e32 v42, v32
	v_fma_f32 v32, v33, v48, v141
	v_mul_f32_e32 v32, 0xbfb8aa3b, v32
	v_exp_f32_e32 v32, v32
	v_fma_f32 v38, v38, v48, v142
	v_fma_f32 v39, v39, v48, v143
	v_mul_f32_e32 v36, 0xbfb8aa3b, v36
	v_add_f32_e32 v32, 1.0, v32
	v_rcp_f32_e32 v43, v32
	v_fma_f32 v32, v34, v48, v138
	v_mul_f32_e32 v32, 0xbfb8aa3b, v32
	v_exp_f32_e32 v32, v32
	v_mul_f32_e32 v37, 0xbfb8aa3b, v37
	v_mul_f32_e32 v38, 0xbfb8aa3b, v38
	v_mul_f32_e32 v39, 0xbfb8aa3b, v39
	v_add_f32_e32 v32, 1.0, v32
	v_rcp_f32_e32 v44, v32
	v_fma_f32 v32, v35, v48, v139
	v_mul_f32_e32 v32, 0xbfb8aa3b, v32
	v_exp_f32_e32 v32, v32
	v_exp_f32_e32 v36, v36
	v_exp_f32_e32 v37, v37
	v_exp_f32_e32 v38, v38
	v_exp_f32_e32 v39, v39
	v_add_f32_e32 v32, 1.0, v32
	v_add_f32_e32 v36, 1.0, v36
	v_add_f32_e32 v37, 1.0, v37
	v_add_f32_e32 v38, 1.0, v38
	v_add_f32_e32 v39, 1.0, v39
	v_rcp_f32_e32 v35, v32
	v_rcp_f32_e32 v36, v36
	v_rcp_f32_e32 v37, v37
	v_rcp_f32_e32 v38, v38
	v_rcp_f32_e32 v39, v39
	v_cvt_pk_bf16_f32 v32, v36, v37
	v_cvt_pk_bf16_f32 v33, v38, v39
	v_cvt_pk_bf16_f32 v34, v42, v43
	v_cvt_pk_bf16_f32 v35, v44, v35
	global_store_dwordx4 v[40:41], v[32:35], off offset:256
	s_nop 0
	s_nop 0
	v_add_u32_e32 v34, 0xa0, v156
	v_ashrrev_i32_e32 v35, 31, v34
	v_lshlrev_b64 v[34:35], 11, v[34:35]
	v_fmamk_f32 v32, v194, 0x3a800000, v204
	v_rsq_f32_e32 v32, v32
	s_nop 0
	v_fma_f32 v26, v26, v32, v146
	v_mul_f32_e32 v26, 0xbfb8aa3b, v26
	v_exp_f32_e32 v26, v26
	v_fma_f32 v28, v28, v32, v152
	v_fma_f32 v24, v24, v32, v148
	v_fma_f32 v25, v25, v32, v149
	v_add_f32_e32 v26, 1.0, v26
	v_mul_f32_e32 v28, 0xbfb8aa3b, v28
	v_fma_f32 v29, v29, v32, v153
	v_fma_f32 v30, v30, v32, v150
	v_fma_f32 v31, v31, v32, v151
	v_mul_f32_e32 v24, 0xbfb8aa3b, v24
	v_mul_f32_e32 v25, 0xbfb8aa3b, v25
	v_rcp_f32_e32 v33, v26
	v_fma_f32 v26, v27, v32, v147
	v_exp_f32_e32 v28, v28
	v_mul_f32_e32 v29, 0xbfb8aa3b, v29
	v_mul_f32_e32 v30, 0xbfb8aa3b, v30
	v_mul_f32_e32 v31, 0xbfb8aa3b, v31
	v_exp_f32_e32 v24, v24
	v_exp_f32_e32 v25, v25
	v_mul_f32_e32 v26, 0xbfb8aa3b, v26
	v_exp_f32_e32 v29, v29
	v_exp_f32_e32 v30, v30
	v_exp_f32_e32 v31, v31
	v_exp_f32_e32 v26, v26
	v_fma_f32 v16, v16, v32, v140
	v_mul_f32_e32 v16, 0xbfb8aa3b, v16
	v_exp_f32_e32 v16, v16
	v_add_f32_e32 v28, 1.0, v28
	v_add_f32_e32 v24, 1.0, v24
	v_add_f32_e32 v25, 1.0, v25
	v_rcp_f32_e32 v28, v28
	v_add_f32_e32 v29, 1.0, v29
	v_add_f32_e32 v30, 1.0, v30
	v_add_f32_e32 v31, 1.0, v31
	v_rcp_f32_e32 v24, v24
	v_rcp_f32_e32 v25, v25
	v_add_f32_e32 v26, 1.0, v26
	v_rcp_f32_e32 v29, v29
	v_rcp_f32_e32 v30, v30
	v_rcp_f32_e32 v31, v31
	v_rcp_f32_e32 v36, v26
	v_cvt_pk_bf16_f32 v26, v28, v29
	v_cvt_pk_bf16_f32 v27, v30, v31
	v_cvt_pk_bf16_f32 v28, v24, v25
	v_lshl_add_u64 v[24:25], s[70:71], 0, v[34:35]
	v_lshl_add_u64 v[24:25], v[24:25], 0, v[120:121]
	v_add_f32_e32 v16, 1.0, v16
	v_cvt_pk_bf16_f32 v29, v33, v36
	global_store_dwordx4 v[24:25], v[26:29], off
	v_fma_f32 v20, v20, v32, v144
	v_fma_f32 v21, v21, v32, v145
	v_rcp_f32_e32 v26, v16
	v_fma_f32 v16, v17, v32, v141
	v_mul_f32_e32 v16, 0xbfb8aa3b, v16
	v_exp_f32_e32 v16, v16
	v_fma_f32 v22, v22, v32, v142
	v_fma_f32 v23, v23, v32, v143
	v_mul_f32_e32 v20, 0xbfb8aa3b, v20
	v_add_f32_e32 v16, 1.0, v16
	v_rcp_f32_e32 v27, v16
	v_fma_f32 v16, v18, v32, v138
	v_mul_f32_e32 v16, 0xbfb8aa3b, v16
	v_exp_f32_e32 v16, v16
	v_mul_f32_e32 v21, 0xbfb8aa3b, v21
	v_mul_f32_e32 v22, 0xbfb8aa3b, v22
	v_mul_f32_e32 v23, 0xbfb8aa3b, v23
	v_add_f32_e32 v16, 1.0, v16
	v_rcp_f32_e32 v28, v16
	v_fma_f32 v16, v19, v32, v139
	v_mul_f32_e32 v16, 0xbfb8aa3b, v16
	v_exp_f32_e32 v16, v16
	v_exp_f32_e32 v20, v20
	v_exp_f32_e32 v21, v21
	v_exp_f32_e32 v22, v22
	v_exp_f32_e32 v23, v23
	v_add_f32_e32 v16, 1.0, v16
	v_add_f32_e32 v20, 1.0, v20
	v_add_f32_e32 v21, 1.0, v21
	v_add_f32_e32 v22, 1.0, v22
	v_add_f32_e32 v23, 1.0, v23
	v_rcp_f32_e32 v19, v16
	v_rcp_f32_e32 v20, v20
	v_rcp_f32_e32 v21, v21
	v_rcp_f32_e32 v22, v22
	v_rcp_f32_e32 v23, v23
	v_cvt_pk_bf16_f32 v16, v20, v21
	v_cvt_pk_bf16_f32 v17, v22, v23
	v_cvt_pk_bf16_f32 v18, v26, v27
	v_cvt_pk_bf16_f32 v19, v28, v19
	global_store_dwordx4 v[24:25], v[16:19], off offset:256
	s_nop 0
	s_nop 0
	v_add_u32_e32 v18, 0xb0, v156
	v_ashrrev_i32_e32 v19, 31, v18
	v_lshlrev_b64 v[18:19], 11, v[18:19]
	v_fmamk_f32 v16, v195, 0x3a800000, v204
	v_rsq_f32_e32 v16, v16
	s_nop 0
	v_fma_f32 v10, v10, v16, v146
	v_mul_f32_e32 v10, 0xbfb8aa3b, v10
	v_exp_f32_e32 v10, v10
	v_fma_f32 v12, v12, v16, v152
	v_fma_f32 v8, v8, v16, v148
	v_fmac_f32_e32 v149, v9, v16
	v_mul_f32_e32 v12, 0xbfb8aa3b, v12
	v_fmac_f32_e32 v153, v13, v16
	v_fma_f32 v14, v14, v16, v150
	v_fmac_f32_e32 v151, v15, v16
	v_mul_f32_e32 v8, 0xbfb8aa3b, v8
	v_mul_f32_e32 v9, 0xbfb8aa3b, v149
	v_add_f32_e32 v10, 1.0, v10
	v_fmac_f32_e32 v147, v11, v16
	v_exp_f32_e32 v12, v12
	v_mul_f32_e32 v13, 0xbfb8aa3b, v153
	v_mul_f32_e32 v14, 0xbfb8aa3b, v14
	v_mul_f32_e32 v15, 0xbfb8aa3b, v151
	v_exp_f32_e32 v8, v8
	v_exp_f32_e32 v9, v9
	v_rcp_f32_e32 v17, v10
	v_mul_f32_e32 v10, 0xbfb8aa3b, v147
	v_exp_f32_e32 v13, v13
	v_exp_f32_e32 v14, v14
	v_exp_f32_e32 v15, v15
	v_exp_f32_e32 v10, v10
	v_fma_f32 v0, v0, v16, v140
	v_mul_f32_e32 v0, 0xbfb8aa3b, v0
	v_exp_f32_e32 v0, v0
	v_add_f32_e32 v12, 1.0, v12
	v_add_f32_e32 v8, 1.0, v8
	v_add_f32_e32 v9, 1.0, v9
	v_rcp_f32_e32 v12, v12
	v_add_f32_e32 v13, 1.0, v13
	v_add_f32_e32 v14, 1.0, v14
	v_add_f32_e32 v15, 1.0, v15
	v_rcp_f32_e32 v8, v8
	v_rcp_f32_e32 v9, v9
	v_add_f32_e32 v10, 1.0, v10
	v_rcp_f32_e32 v13, v13
	v_rcp_f32_e32 v14, v14
	v_rcp_f32_e32 v15, v15
	v_rcp_f32_e32 v20, v10
	v_cvt_pk_bf16_f32 v10, v12, v13
	v_cvt_pk_bf16_f32 v11, v14, v15
	v_cvt_pk_bf16_f32 v12, v8, v9
	v_lshl_add_u64 v[8:9], s[70:71], 0, v[18:19]
	v_lshl_add_u64 v[8:9], v[8:9], 0, v[120:121]
	v_add_f32_e32 v0, 1.0, v0
	v_fmac_f32_e32 v141, v1, v16
	v_cvt_pk_bf16_f32 v13, v17, v20
	global_store_dwordx4 v[8:9], v[10:13], off
	v_fmac_f32_e32 v139, v3, v16
	v_fma_f32 v4, v4, v16, v144
	v_rcp_f32_e32 v10, v0
	v_mul_f32_e32 v0, 0xbfb8aa3b, v141
	v_exp_f32_e32 v0, v0
	v_fmac_f32_e32 v145, v5, v16
	v_fma_f32 v6, v6, v16, v142
	v_fmac_f32_e32 v143, v7, v16
	v_add_f32_e32 v0, 1.0, v0
	v_rcp_f32_e32 v11, v0
	v_fma_f32 v0, v2, v16, v138
	v_mul_f32_e32 v0, 0xbfb8aa3b, v0
	v_exp_f32_e32 v0, v0
	v_mul_f32_e32 v4, 0xbfb8aa3b, v4
	v_mul_f32_e32 v5, 0xbfb8aa3b, v145
	v_mul_f32_e32 v6, 0xbfb8aa3b, v6
	v_add_f32_e32 v0, 1.0, v0
	v_rcp_f32_e32 v12, v0
	v_mul_f32_e32 v0, 0xbfb8aa3b, v139
	v_mul_f32_e32 v7, 0xbfb8aa3b, v143
	v_exp_f32_e32 v0, v0
	v_exp_f32_e32 v4, v4
	v_exp_f32_e32 v5, v5
	v_exp_f32_e32 v6, v6
	v_exp_f32_e32 v7, v7
	v_add_f32_e32 v0, 1.0, v0
	v_add_f32_e32 v4, 1.0, v4
	v_add_f32_e32 v5, 1.0, v5
	v_add_f32_e32 v6, 1.0, v6
	v_add_f32_e32 v7, 1.0, v7
	v_rcp_f32_e32 v3, v0
	v_rcp_f32_e32 v4, v4
	v_rcp_f32_e32 v5, v5
	v_rcp_f32_e32 v6, v6
	v_rcp_f32_e32 v7, v7
	v_cvt_pk_bf16_f32 v0, v4, v5
	v_cvt_pk_bf16_f32 v1, v6, v7
	v_cvt_pk_bf16_f32 v2, v10, v11
	v_cvt_pk_bf16_f32 v3, v12, v3
	global_store_dwordx4 v[8:9], v[0:3], off offset:256
	s_cbranch_vccnz .LBB0_509
	s_andn2_b64 vcc, exec, s[6:7]
	s_cbranch_vccnz .LBB0_508
	s_barrier
	s_branch .LBB0_508

.LBB0_728:
	s_ashr_i32 s18, s2, 4
	s_ashr_i32 s19, s18, 31
	s_lshl_b64 s[18:19], s[18:19], 14
	v_lshl_or_b32 v162, s3, 8, v158
	s_add_u32 s18, s31, s18
	v_lshl_add_u32 v154, s2, 8, v156
	s_addc_u32 s19, s34, s19
	v_ashrrev_i32_e32 v163, 31, v162
	v_ashrrev_i32_e32 v155, 31, v154
	v_lshl_add_u64 v[36:37], v[162:163], 2, s[18:19]
	v_lshl_add_u64 v[166:167], v[154:155], 2, s[50:51]
	global_load_dwordx4 v[40:43], v[36:37], off offset:16
	global_load_dwordx4 v[44:47], v[36:37], off
	global_load_dwordx4 v[32:35], v[36:37], off offset:528
	s_nop 0
	global_load_dwordx4 v[36:39], v[36:37], off offset:512
	v_lshlrev_b64 v[168:169], 13, v[154:155]
	global_load_dword v170, v[166:167], off
	global_load_dword v171, v[166:167], off offset:64
	global_load_dword v172, v[166:167], off offset:128
	global_load_dword v173, v[166:167], off offset:192
	global_load_dword v174, v[166:167], off offset:512
	global_load_dword v175, v[166:167], off offset:576
	global_load_dword v176, v[166:167], off offset:640
	global_load_dword v177, v[166:167], off offset:704
	s_mov_b64 s[18:19], -1
	s_andn2_b64 vcc, exec, s[4:5]
	s_waitcnt vmcnt(0)
	v_fmamk_f32 v166, v170, 0x3a800000, v204
	v_rsq_f32_e32 v166, v166
	s_nop 0
	v_pk_fma_f32 v[138:139], v[138:139], v[166:167], v[42:43] op_sel_hi:[1,0,1]
	v_pk_fma_f32 v[142:143], v[142:143], v[166:167], v[46:47] op_sel_hi:[1,0,1]
	v_pk_fma_f32 v[140:141], v[140:141], v[166:167], v[44:45] op_sel_hi:[1,0,1]
	v_pk_fma_f32 v[136:137], v[136:137], v[166:167], v[40:41] op_sel_hi:[1,0,1]
	v_max_f32_e32 v138, 0, v138
	v_max_f32_e32 v140, 0, v140
	v_max_f32_e32 v142, 0, v142
	v_max_f32_e32 v143, 0, v143
	v_max_f32_e32 v136, 0, v136
	v_max_f32_e32 v137, 0, v137
	v_mul_f32_e32 v155, v138, v138
	v_max_f32_e32 v138, 0, v139
	v_mul_f32_e32 v140, v140, v140
	v_max_f32_e32 v141, 0, v141
	v_mul_f32_e32 v142, v142, v142
	v_mul_f32_e32 v143, v143, v143
	v_mul_f32_e32 v136, v136, v136
	v_mul_f32_e32 v137, v137, v137
	v_mul_f32_e32 v167, v138, v138
	v_mul_f32_e32 v141, v141, v141
	v_cvt_pk_bf16_f32 v138, v140, v141
	v_cvt_pk_bf16_f32 v139, v142, v143
	v_cvt_pk_bf16_f32 v140, v136, v137
	v_lshl_add_u64 v[142:143], s[62:63], 0, v[168:169]
	v_lshlrev_b64 v[136:137], 1, v[162:163]
	v_pk_fma_f32 v[128:129], v[128:129], v[166:167], v[32:33] op_sel_hi:[1,0,1]
	v_lshl_add_u64 v[142:143], v[142:143], 0, v[136:137]
	v_max_f32_e32 v128, 0, v128
	v_cvt_pk_bf16_f32 v141, v155, v167
	global_store_dwordx4 v[142:143], v[138:141], off
	v_pk_fma_f32 v[130:131], v[130:131], v[166:167], v[34:35] op_sel_hi:[1,0,1]
	v_pk_fma_f32 v[132:133], v[132:133], v[166:167], v[36:37] op_sel_hi:[1,0,1]
	v_mul_f32_e32 v138, v128, v128
	v_max_f32_e32 v128, 0, v129
	v_mul_f32_e32 v139, v128, v128
	v_max_f32_e32 v128, 0, v130
	v_pk_fma_f32 v[134:135], v[134:135], v[166:167], v[38:39] op_sel_hi:[1,0,1]
	v_max_f32_e32 v132, 0, v132
	v_max_f32_e32 v133, 0, v133
	v_mul_f32_e32 v140, v128, v128
	v_max_f32_e32 v128, 0, v131
	v_mul_f32_e32 v132, v132, v132
	v_mul_f32_e32 v133, v133, v133
	v_max_f32_e32 v134, 0, v134
	v_max_f32_e32 v135, 0, v135
	v_mul_f32_e32 v131, v128, v128
	v_cvt_pk_bf16_f32 v128, v132, v133
	v_mul_f32_e32 v134, v134, v134
	v_mul_f32_e32 v135, v135, v135
	v_cvt_pk_bf16_f32 v129, v134, v135
	v_cvt_pk_bf16_f32 v130, v138, v139
	v_cvt_pk_bf16_f32 v131, v140, v131
	global_store_dwordx4 v[142:143], v[128:131], off offset:256
	s_nop 1
	v_or_b32_e32 v128, 16, v154
	v_ashrrev_i32_e32 v129, 31, v128
	v_lshlrev_b64 v[128:129], 13, v[128:129]
	v_fmamk_f32 v130, v171, 0x3a800000, v204
	v_rsq_f32_e32 v130, v130
	s_nop 0
	v_pk_fma_f32 v[120:121], v[120:121], v[130:131], v[40:41] op_sel_hi:[1,0,1]
	s_nop 0
	v_max_f32_e32 v120, 0, v120
	v_pk_fma_f32 v[126:127], v[126:127], v[130:131], v[46:47] op_sel_hi:[1,0,1]
	v_pk_fma_f32 v[124:125], v[124:125], v[130:131], v[44:45] op_sel_hi:[1,0,1]
	v_pk_fma_f32 v[122:123], v[122:123], v[130:131], v[42:43] op_sel_hi:[1,0,1]
	v_mul_f32_e32 v131, v120, v120
	v_max_f32_e32 v120, 0, v121
	v_max_f32_e32 v124, 0, v124
	v_max_f32_e32 v125, 0, v125
	v_mul_f32_e32 v132, v120, v120
	v_max_f32_e32 v120, 0, v122
	v_mul_f32_e32 v124, v124, v124
	v_mul_f32_e32 v125, v125, v125
	v_mul_f32_e32 v133, v120, v120
	v_max_f32_e32 v120, 0, v123
	v_mul_f32_e32 v123, v120, v120
	v_cvt_pk_bf16_f32 v120, v124, v125
	v_lshl_add_u64 v[124:125], s[62:63], 0, v[128:129]
	v_pk_fma_f32 v[112:113], v[112:113], v[130:131], v[32:33] op_sel_hi:[1,0,1]
	v_max_f32_e32 v126, 0, v126
	v_max_f32_e32 v127, 0, v127
	v_lshl_add_u64 v[124:125], v[124:125], 0, v[136:137]
	v_max_f32_e32 v112, 0, v112
	v_mul_f32_e32 v126, v126, v126
	v_mul_f32_e32 v127, v127, v127
	v_cvt_pk_bf16_f32 v121, v126, v127
	v_cvt_pk_bf16_f32 v122, v131, v132
	v_cvt_pk_bf16_f32 v123, v133, v123
	global_store_dwordx4 v[124:125], v[120:123], off
	v_pk_fma_f32 v[114:115], v[114:115], v[130:131], v[34:35] op_sel_hi:[1,0,1]
	v_pk_fma_f32 v[116:117], v[116:117], v[130:131], v[36:37] op_sel_hi:[1,0,1]
	v_mul_f32_e32 v120, v112, v112
	v_max_f32_e32 v112, 0, v113
	v_mul_f32_e32 v121, v112, v112
	v_max_f32_e32 v112, 0, v114
	v_pk_fma_f32 v[118:119], v[118:119], v[130:131], v[38:39] op_sel_hi:[1,0,1]
	v_max_f32_e32 v116, 0, v116
	v_max_f32_e32 v117, 0, v117
	v_mul_f32_e32 v122, v112, v112
	v_max_f32_e32 v112, 0, v115
	v_mul_f32_e32 v116, v116, v116
	v_mul_f32_e32 v117, v117, v117
	v_max_f32_e32 v118, 0, v118
	v_max_f32_e32 v119, 0, v119
	v_mul_f32_e32 v115, v112, v112
	v_cvt_pk_bf16_f32 v112, v116, v117
	v_mul_f32_e32 v118, v118, v118
	v_mul_f32_e32 v119, v119, v119
	v_cvt_pk_bf16_f32 v113, v118, v119
	v_cvt_pk_bf16_f32 v114, v120, v121
	v_cvt_pk_bf16_f32 v115, v122, v115
	global_store_dwordx4 v[124:125], v[112:115], off offset:256
	s_nop 1
	v_or_b32_e32 v112, 32, v154
	v_ashrrev_i32_e32 v113, 31, v112
	v_lshlrev_b64 v[112:113], 13, v[112:113]
	v_fmamk_f32 v114, v172, 0x3a800000, v204
	v_rsq_f32_e32 v114, v114
	s_nop 0
	v_pk_fma_f32 v[104:105], v[104:105], v[114:115], v[40:41] op_sel_hi:[1,0,1]
	s_nop 0
	v_max_f32_e32 v104, 0, v104
	v_pk_fma_f32 v[110:111], v[110:111], v[114:115], v[46:47] op_sel_hi:[1,0,1]
	v_pk_fma_f32 v[108:109], v[108:109], v[114:115], v[44:45] op_sel_hi:[1,0,1]
	v_pk_fma_f32 v[106:107], v[106:107], v[114:115], v[42:43] op_sel_hi:[1,0,1]
	v_mul_f32_e32 v115, v104, v104
	v_max_f32_e32 v104, 0, v105
	v_max_f32_e32 v108, 0, v108
	v_max_f32_e32 v109, 0, v109
	v_mul_f32_e32 v116, v104, v104
	v_max_f32_e32 v104, 0, v106
	v_mul_f32_e32 v108, v108, v108
	v_mul_f32_e32 v109, v109, v109
	v_mul_f32_e32 v117, v104, v104
	v_max_f32_e32 v104, 0, v107
	v_mul_f32_e32 v107, v104, v104
	v_cvt_pk_bf16_f32 v104, v108, v109
	v_lshl_add_u64 v[108:109], s[62:63], 0, v[112:113]
	v_pk_fma_f32 v[96:97], v[96:97], v[114:115], v[32:33] op_sel_hi:[1,0,1]
	v_max_f32_e32 v110, 0, v110
	v_max_f32_e32 v111, 0, v111
	v_lshl_add_u64 v[108:109], v[108:109], 0, v[136:137]
	v_max_f32_e32 v96, 0, v96
	v_mul_f32_e32 v110, v110, v110
	v_mul_f32_e32 v111, v111, v111
	v_cvt_pk_bf16_f32 v105, v110, v111
	v_cvt_pk_bf16_f32 v106, v115, v116
	v_cvt_pk_bf16_f32 v107, v117, v107
	global_store_dwordx4 v[108:109], v[104:107], off
	v_pk_fma_f32 v[98:99], v[98:99], v[114:115], v[34:35] op_sel_hi:[1,0,1]
	v_pk_fma_f32 v[100:101], v[100:101], v[114:115], v[36:37] op_sel_hi:[1,0,1]
	v_mul_f32_e32 v104, v96, v96
	v_max_f32_e32 v96, 0, v97
	v_mul_f32_e32 v105, v96, v96
	v_max_f32_e32 v96, 0, v98
	v_pk_fma_f32 v[102:103], v[102:103], v[114:115], v[38:39] op_sel_hi:[1,0,1]
	v_max_f32_e32 v100, 0, v100
	v_max_f32_e32 v101, 0, v101
	v_mul_f32_e32 v106, v96, v96
	v_max_f32_e32 v96, 0, v99
	v_mul_f32_e32 v100, v100, v100
	v_mul_f32_e32 v101, v101, v101
	v_max_f32_e32 v102, 0, v102
	v_max_f32_e32 v103, 0, v103
	v_mul_f32_e32 v99, v96, v96
	v_cvt_pk_bf16_f32 v96, v100, v101
	v_mul_f32_e32 v102, v102, v102
	v_mul_f32_e32 v103, v103, v103
	v_cvt_pk_bf16_f32 v97, v102, v103
	v_cvt_pk_bf16_f32 v98, v104, v105
	v_cvt_pk_bf16_f32 v99, v106, v99
	global_store_dwordx4 v[108:109], v[96:99], off offset:256
	s_nop 1
	v_or_b32_e32 v96, 48, v154
	v_ashrrev_i32_e32 v97, 31, v96
	v_lshlrev_b64 v[96:97], 13, v[96:97]
	v_fmamk_f32 v98, v173, 0x3a800000, v204
	v_rsq_f32_e32 v98, v98
	s_nop 0
	v_pk_fma_f32 v[88:89], v[88:89], v[98:99], v[40:41] op_sel_hi:[1,0,1]
	s_nop 0
	v_max_f32_e32 v88, 0, v88
	v_pk_fma_f32 v[94:95], v[94:95], v[98:99], v[46:47] op_sel_hi:[1,0,1]
	v_pk_fma_f32 v[92:93], v[92:93], v[98:99], v[44:45] op_sel_hi:[1,0,1]
	v_pk_fma_f32 v[90:91], v[90:91], v[98:99], v[42:43] op_sel_hi:[1,0,1]
	v_mul_f32_e32 v99, v88, v88
	v_max_f32_e32 v88, 0, v89
	v_max_f32_e32 v92, 0, v92
	v_max_f32_e32 v93, 0, v93
	v_mul_f32_e32 v100, v88, v88
	v_max_f32_e32 v88, 0, v90
	v_mul_f32_e32 v92, v92, v92
	v_mul_f32_e32 v93, v93, v93
	v_mul_f32_e32 v101, v88, v88
	v_max_f32_e32 v88, 0, v91
	v_mul_f32_e32 v91, v88, v88
	v_cvt_pk_bf16_f32 v88, v92, v93
	v_lshl_add_u64 v[92:93], s[62:63], 0, v[96:97]
	v_pk_fma_f32 v[80:81], v[80:81], v[98:99], v[32:33] op_sel_hi:[1,0,1]
	v_max_f32_e32 v94, 0, v94
	v_max_f32_e32 v95, 0, v95
	v_lshl_add_u64 v[92:93], v[92:93], 0, v[136:137]
	v_max_f32_e32 v80, 0, v80
	v_mul_f32_e32 v94, v94, v94
	v_mul_f32_e32 v95, v95, v95
	v_cvt_pk_bf16_f32 v89, v94, v95
	v_cvt_pk_bf16_f32 v90, v99, v100
	v_cvt_pk_bf16_f32 v91, v101, v91
	global_store_dwordx4 v[92:93], v[88:91], off
	v_pk_fma_f32 v[82:83], v[82:83], v[98:99], v[34:35] op_sel_hi:[1,0,1]
	v_pk_fma_f32 v[84:85], v[84:85], v[98:99], v[36:37] op_sel_hi:[1,0,1]
	v_mul_f32_e32 v88, v80, v80
	v_max_f32_e32 v80, 0, v81
	v_mul_f32_e32 v89, v80, v80
	v_max_f32_e32 v80, 0, v82
	v_pk_fma_f32 v[86:87], v[86:87], v[98:99], v[38:39] op_sel_hi:[1,0,1]
	v_max_f32_e32 v84, 0, v84
	v_max_f32_e32 v85, 0, v85
	v_mul_f32_e32 v90, v80, v80
	v_max_f32_e32 v80, 0, v83
	v_mul_f32_e32 v84, v84, v84
	v_mul_f32_e32 v85, v85, v85
	v_max_f32_e32 v86, 0, v86
	v_max_f32_e32 v87, 0, v87
	v_mul_f32_e32 v83, v80, v80
	v_cvt_pk_bf16_f32 v80, v84, v85
	v_mul_f32_e32 v86, v86, v86
	v_mul_f32_e32 v87, v87, v87
	v_cvt_pk_bf16_f32 v81, v86, v87
	v_cvt_pk_bf16_f32 v82, v88, v89
	v_cvt_pk_bf16_f32 v83, v90, v83
	global_store_dwordx4 v[92:93], v[80:83], off offset:256
	s_nop 1
	v_add_u32_e32 v80, 0x80, v154
	v_ashrrev_i32_e32 v81, 31, v80
	v_lshlrev_b64 v[80:81], 13, v[80:81]
	v_fmamk_f32 v82, v174, 0x3a800000, v204
	v_rsq_f32_e32 v82, v82
	s_nop 0
	v_pk_fma_f32 v[72:73], v[72:73], v[82:83], v[40:41] op_sel_hi:[1,0,1]
	s_nop 0
	v_max_f32_e32 v72, 0, v72
	v_pk_fma_f32 v[78:79], v[78:79], v[82:83], v[46:47] op_sel_hi:[1,0,1]
	v_pk_fma_f32 v[76:77], v[76:77], v[82:83], v[44:45] op_sel_hi:[1,0,1]
	v_pk_fma_f32 v[74:75], v[74:75], v[82:83], v[42:43] op_sel_hi:[1,0,1]
	v_mul_f32_e32 v83, v72, v72
	v_max_f32_e32 v72, 0, v73
	v_max_f32_e32 v76, 0, v76
	v_max_f32_e32 v77, 0, v77
	v_mul_f32_e32 v84, v72, v72
	v_max_f32_e32 v72, 0, v74
	v_mul_f32_e32 v76, v76, v76
	v_mul_f32_e32 v77, v77, v77
	v_mul_f32_e32 v85, v72, v72
	v_max_f32_e32 v72, 0, v75
	v_mul_f32_e32 v75, v72, v72
	v_cvt_pk_bf16_f32 v72, v76, v77
	v_lshl_add_u64 v[76:77], s[62:63], 0, v[80:81]
	v_pk_fma_f32 v[64:65], v[64:65], v[82:83], v[32:33] op_sel_hi:[1,0,1]
	v_max_f32_e32 v78, 0, v78
	v_max_f32_e32 v79, 0, v79
	v_lshl_add_u64 v[76:77], v[76:77], 0, v[136:137]
	v_max_f32_e32 v64, 0, v64
	v_mul_f32_e32 v78, v78, v78
	v_mul_f32_e32 v79, v79, v79
	v_cvt_pk_bf16_f32 v73, v78, v79
	v_cvt_pk_bf16_f32 v74, v83, v84
	v_cvt_pk_bf16_f32 v75, v85, v75
	global_store_dwordx4 v[76:77], v[72:75], off
	v_pk_fma_f32 v[66:67], v[66:67], v[82:83], v[34:35] op_sel_hi:[1,0,1]
	v_pk_fma_f32 v[68:69], v[68:69], v[82:83], v[36:37] op_sel_hi:[1,0,1]
	v_mul_f32_e32 v72, v64, v64
	v_max_f32_e32 v64, 0, v65
	v_mul_f32_e32 v73, v64, v64
	v_max_f32_e32 v64, 0, v66
	v_pk_fma_f32 v[70:71], v[70:71], v[82:83], v[38:39] op_sel_hi:[1,0,1]
	v_max_f32_e32 v68, 0, v68
	v_max_f32_e32 v69, 0, v69
	v_mul_f32_e32 v74, v64, v64
	v_max_f32_e32 v64, 0, v67
	v_mul_f32_e32 v68, v68, v68
	v_mul_f32_e32 v69, v69, v69
	v_max_f32_e32 v70, 0, v70
	v_max_f32_e32 v71, 0, v71
	v_mul_f32_e32 v67, v64, v64
	v_cvt_pk_bf16_f32 v64, v68, v69
	v_mul_f32_e32 v70, v70, v70
	v_mul_f32_e32 v71, v71, v71
	v_cvt_pk_bf16_f32 v65, v70, v71
	v_cvt_pk_bf16_f32 v66, v72, v73
	v_cvt_pk_bf16_f32 v67, v74, v67
	global_store_dwordx4 v[76:77], v[64:67], off offset:256
	s_nop 1
	v_add_u32_e32 v64, 0x90, v154
	v_ashrrev_i32_e32 v65, 31, v64
	v_lshlrev_b64 v[64:65], 13, v[64:65]
	v_fmamk_f32 v66, v175, 0x3a800000, v204
	v_rsq_f32_e32 v66, v66
	s_nop 0
	v_pk_fma_f32 v[56:57], v[56:57], v[66:67], v[40:41] op_sel_hi:[1,0,1]
	s_nop 0
	v_max_f32_e32 v56, 0, v56
	v_pk_fma_f32 v[62:63], v[62:63], v[66:67], v[46:47] op_sel_hi:[1,0,1]
	v_pk_fma_f32 v[60:61], v[60:61], v[66:67], v[44:45] op_sel_hi:[1,0,1]
	v_pk_fma_f32 v[58:59], v[58:59], v[66:67], v[42:43] op_sel_hi:[1,0,1]
	v_mul_f32_e32 v67, v56, v56
	v_max_f32_e32 v56, 0, v57
	v_max_f32_e32 v60, 0, v60
	v_max_f32_e32 v61, 0, v61
	v_mul_f32_e32 v68, v56, v56
	v_max_f32_e32 v56, 0, v58
	v_mul_f32_e32 v60, v60, v60
	v_mul_f32_e32 v61, v61, v61
	v_mul_f32_e32 v69, v56, v56
	v_max_f32_e32 v56, 0, v59
	v_mul_f32_e32 v59, v56, v56
	v_cvt_pk_bf16_f32 v56, v60, v61
	v_lshl_add_u64 v[60:61], s[62:63], 0, v[64:65]
	v_pk_fma_f32 v[48:49], v[48:49], v[66:67], v[32:33] op_sel_hi:[1,0,1]
	v_max_f32_e32 v62, 0, v62
	v_max_f32_e32 v63, 0, v63
	v_lshl_add_u64 v[60:61], v[60:61], 0, v[136:137]
	v_max_f32_e32 v48, 0, v48
	v_mul_f32_e32 v62, v62, v62
	v_mul_f32_e32 v63, v63, v63
	v_cvt_pk_bf16_f32 v57, v62, v63
	v_cvt_pk_bf16_f32 v58, v67, v68
	v_cvt_pk_bf16_f32 v59, v69, v59
	global_store_dwordx4 v[60:61], v[56:59], off
	v_pk_fma_f32 v[50:51], v[50:51], v[66:67], v[34:35] op_sel_hi:[1,0,1]
	v_pk_fma_f32 v[52:53], v[52:53], v[66:67], v[36:37] op_sel_hi:[1,0,1]
	v_mul_f32_e32 v56, v48, v48
	v_max_f32_e32 v48, 0, v49
	v_mul_f32_e32 v57, v48, v48
	v_max_f32_e32 v48, 0, v50
	v_pk_fma_f32 v[54:55], v[54:55], v[66:67], v[38:39] op_sel_hi:[1,0,1]
	v_max_f32_e32 v52, 0, v52
	v_max_f32_e32 v53, 0, v53
	v_mul_f32_e32 v58, v48, v48
	v_max_f32_e32 v48, 0, v51
	v_mul_f32_e32 v52, v52, v52
	v_mul_f32_e32 v53, v53, v53
	v_max_f32_e32 v54, 0, v54
	v_max_f32_e32 v55, 0, v55
	v_mul_f32_e32 v51, v48, v48
	v_cvt_pk_bf16_f32 v48, v52, v53
	v_mul_f32_e32 v54, v54, v54
	v_mul_f32_e32 v55, v55, v55
	v_cvt_pk_bf16_f32 v49, v54, v55
	v_cvt_pk_bf16_f32 v50, v56, v57
	v_cvt_pk_bf16_f32 v51, v58, v51
	global_store_dwordx4 v[60:61], v[48:51], off offset:256
	s_nop 1
	v_add_u32_e32 v48, 0xa0, v154
	v_ashrrev_i32_e32 v49, 31, v48
	v_lshlrev_b64 v[48:49], 13, v[48:49]
	v_fmamk_f32 v50, v176, 0x3a800000, v204
	v_rsq_f32_e32 v50, v50
	s_nop 0
	v_pk_fma_f32 v[24:25], v[24:25], v[50:51], v[40:41] op_sel_hi:[1,0,1]
	s_nop 0
	v_max_f32_e32 v24, 0, v24
	v_pk_fma_f32 v[30:31], v[30:31], v[50:51], v[46:47] op_sel_hi:[1,0,1]
	v_pk_fma_f32 v[28:29], v[28:29], v[50:51], v[44:45] op_sel_hi:[1,0,1]
	v_pk_fma_f32 v[26:27], v[26:27], v[50:51], v[42:43] op_sel_hi:[1,0,1]
	v_mul_f32_e32 v51, v24, v24
	v_max_f32_e32 v24, 0, v25
	v_max_f32_e32 v28, 0, v28
	v_max_f32_e32 v29, 0, v29
	v_mul_f32_e32 v52, v24, v24
	v_max_f32_e32 v24, 0, v26
	v_mul_f32_e32 v28, v28, v28
	v_mul_f32_e32 v29, v29, v29
	v_mul_f32_e32 v53, v24, v24
	v_max_f32_e32 v24, 0, v27
	v_mul_f32_e32 v27, v24, v24
	v_cvt_pk_bf16_f32 v24, v28, v29
	v_lshl_add_u64 v[28:29], s[62:63], 0, v[48:49]
	v_pk_fma_f32 v[16:17], v[16:17], v[50:51], v[32:33] op_sel_hi:[1,0,1]
	v_max_f32_e32 v30, 0, v30
	v_max_f32_e32 v31, 0, v31
	v_lshl_add_u64 v[28:29], v[28:29], 0, v[136:137]
	v_max_f32_e32 v16, 0, v16
	v_mul_f32_e32 v30, v30, v30
	v_mul_f32_e32 v31, v31, v31
	v_cvt_pk_bf16_f32 v25, v30, v31
	v_cvt_pk_bf16_f32 v26, v51, v52
	v_cvt_pk_bf16_f32 v27, v53, v27
	global_store_dwordx4 v[28:29], v[24:27], off
	v_pk_fma_f32 v[18:19], v[18:19], v[50:51], v[34:35] op_sel_hi:[1,0,1]
	v_pk_fma_f32 v[20:21], v[20:21], v[50:51], v[36:37] op_sel_hi:[1,0,1]
	v_mul_f32_e32 v24, v16, v16
	v_max_f32_e32 v16, 0, v17
	v_mul_f32_e32 v25, v16, v16
	v_max_f32_e32 v16, 0, v18
	v_pk_fma_f32 v[22:23], v[22:23], v[50:51], v[38:39] op_sel_hi:[1,0,1]
	v_max_f32_e32 v20, 0, v20
	v_max_f32_e32 v21, 0, v21
	v_mul_f32_e32 v26, v16, v16
	v_max_f32_e32 v16, 0, v19
	v_mul_f32_e32 v20, v20, v20
	v_mul_f32_e32 v21, v21, v21
	v_max_f32_e32 v22, 0, v22
	v_max_f32_e32 v23, 0, v23
	v_mul_f32_e32 v19, v16, v16
	v_cvt_pk_bf16_f32 v16, v20, v21
	v_mul_f32_e32 v22, v22, v22
	v_mul_f32_e32 v23, v23, v23
	v_cvt_pk_bf16_f32 v17, v22, v23
	v_cvt_pk_bf16_f32 v18, v24, v25
	v_cvt_pk_bf16_f32 v19, v26, v19
	global_store_dwordx4 v[28:29], v[16:19], off offset:256
	s_nop 1
	v_add_u32_e32 v16, 0xb0, v154
	v_ashrrev_i32_e32 v17, 31, v16
	v_lshlrev_b64 v[16:17], 13, v[16:17]
	v_fmamk_f32 v18, v177, 0x3a800000, v204
	v_rsq_f32_e32 v18, v18
	s_nop 0
	v_pk_fma_f32 v[8:9], v[8:9], v[18:19], v[40:41] op_sel_hi:[1,0,1]
	s_nop 0
	v_max_f32_e32 v8, 0, v8
	v_pk_fma_f32 v[14:15], v[14:15], v[18:19], v[46:47] op_sel_hi:[1,0,1]
	v_pk_fma_f32 v[12:13], v[12:13], v[18:19], v[44:45] op_sel_hi:[1,0,1]
	v_pk_fma_f32 v[10:11], v[10:11], v[18:19], v[42:43] op_sel_hi:[1,0,1]
	v_mul_f32_e32 v19, v8, v8
	v_max_f32_e32 v8, 0, v9
	v_max_f32_e32 v12, 0, v12
	v_max_f32_e32 v13, 0, v13
	v_mul_f32_e32 v20, v8, v8
	v_max_f32_e32 v8, 0, v10
	v_mul_f32_e32 v12, v12, v12
	v_mul_f32_e32 v13, v13, v13
	v_mul_f32_e32 v21, v8, v8
	v_max_f32_e32 v8, 0, v11
	v_mul_f32_e32 v11, v8, v8
	v_cvt_pk_bf16_f32 v8, v12, v13
	v_lshl_add_u64 v[12:13], s[62:63], 0, v[16:17]
	v_pk_fma_f32 v[0:1], v[0:1], v[18:19], v[32:33] op_sel_hi:[1,0,1]
	v_max_f32_e32 v14, 0, v14
	v_max_f32_e32 v15, 0, v15
	v_lshl_add_u64 v[12:13], v[12:13], 0, v[136:137]
	v_max_f32_e32 v0, 0, v0
	v_mul_f32_e32 v14, v14, v14
	v_mul_f32_e32 v15, v15, v15
	v_cvt_pk_bf16_f32 v9, v14, v15
	v_cvt_pk_bf16_f32 v10, v19, v20
	v_cvt_pk_bf16_f32 v11, v21, v11
	global_store_dwordx4 v[12:13], v[8:11], off
	v_pk_fma_f32 v[2:3], v[2:3], v[18:19], v[34:35] op_sel_hi:[1,0,1]
	v_pk_fma_f32 v[6:7], v[6:7], v[18:19], v[38:39] op_sel_hi:[1,0,1]
	v_mul_f32_e32 v8, v0, v0
	v_max_f32_e32 v0, 0, v1
	v_mul_f32_e32 v9, v0, v0
	v_max_f32_e32 v0, 0, v2
	v_pk_fma_f32 v[4:5], v[4:5], v[18:19], v[36:37] op_sel_hi:[1,0,1]
	v_mul_f32_e32 v10, v0, v0
	v_max_f32_e32 v0, 0, v3
	v_max_f32_e32 v4, 0, v4
	v_max_f32_e32 v5, 0, v5
	v_max_f32_e32 v6, 0, v6
	v_max_f32_e32 v7, 0, v7
	v_mul_f32_e32 v3, v0, v0
	v_mul_f32_e32 v4, v4, v4
	v_mul_f32_e32 v5, v5, v5
	v_mul_f32_e32 v6, v6, v6
	v_mul_f32_e32 v7, v7, v7
	v_cvt_pk_bf16_f32 v0, v4, v5
	v_cvt_pk_bf16_f32 v1, v6, v7
	v_cvt_pk_bf16_f32 v2, v8, v9
	v_cvt_pk_bf16_f32 v3, v10, v3
	global_store_dwordx4 v[12:13], v[0:3], off offset:256
	s_cbranch_vccnz .LBB0_717
	s_andn2_b64 vcc, exec, s[0:1]
	s_cbranch_vccnz .LBB0_716
	s_barrier
	s_branch .LBB0_716

	.amdhsa_kernel _Z14fwd_megakernel4Args
		.amdhsa_group_segment_fixed_size 0
		.amdhsa_private_segment_fixed_size 0
		.amdhsa_kernarg_size 416
		.amdhsa_user_sgpr_count 2
		.amdhsa_user_sgpr_dispatch_ptr 0
		.amdhsa_user_sgpr_queue_ptr 0
		.amdhsa_user_sgpr_kernarg_segment_ptr 1
		.amdhsa_user_sgpr_dispatch_id 0
		.amdhsa_user_sgpr_kernarg_preload_length 0
		.amdhsa_user_sgpr_kernarg_preload_offset 0
		.amdhsa_user_sgpr_private_segment_size 0
		.amdhsa_uses_dynamic_stack 0
		.amdhsa_enable_private_segment 0
		.amdhsa_system_sgpr_workgroup_id_x 1
		.amdhsa_system_sgpr_workgroup_id_y 0
		.amdhsa_system_sgpr_workgroup_id_z 0
		.amdhsa_system_sgpr_workgroup_info 0
		.amdhsa_system_vgpr_workitem_id 2
		.amdhsa_next_free_vgpr 256
		.amdhsa_next_free_sgpr 100
		.amdhsa_accum_offset 256
		.amdhsa_reserve_vcc 1
		.amdhsa_float_round_mode_32 0
		.amdhsa_float_round_mode_16_64 0
		.amdhsa_float_denorm_mode_32 3
		.amdhsa_float_denorm_mode_16_64 3
		.amdhsa_dx10_clamp 1
		.amdhsa_ieee_mode 1
		.amdhsa_fp16_overflow 0
		.amdhsa_tg_split 0
		.amdhsa_exception_fp_ieee_invalid_op 0
		.amdhsa_exception_fp_denorm_src 0
		.amdhsa_exception_fp_ieee_div_zero 0
		.amdhsa_exception_fp_ieee_overflow 0
		.amdhsa_exception_fp_ieee_underflow 0
		.amdhsa_exception_fp_ieee_inexact 0
		.amdhsa_exception_int_div_zero 0
	.end_amdhsa_kernel

amdhsa.kernels:
  - .agpr_count:     0
    .args:
      - .offset:         0
        .size:           160
        .value_kind:     by_value
      - .offset:         160
        .size:           4
        .value_kind:     hidden_block_count_x
      - .offset:         164
        .size:           4
        .value_kind:     hidden_block_count_y
      - .offset:         168
        .size:           4
        .value_kind:     hidden_block_count_z
      - .offset:         172
        .size:           2
        .value_kind:     hidden_group_size_x
      - .offset:         174
        .size:           2
        .value_kind:     hidden_group_size_y
      - .offset:         176
        .size:           2
        .value_kind:     hidden_group_size_z
      - .offset:         178
        .size:           2
        .value_kind:     hidden_remainder_x
      - .offset:         180
        .size:           2
        .value_kind:     hidden_remainder_y
      - .offset:         182
        .size:           2
        .value_kind:     hidden_remainder_z
      - .offset:         200
        .size:           8
        .value_kind:     hidden_global_offset_x
      - .offset:         208
        .size:           8
        .value_kind:     hidden_global_offset_y
      - .offset:         216
        .size:           8
        .value_kind:     hidden_global_offset_z
      - .offset:         224
        .size:           2
        .value_kind:     hidden_grid_dims
      - .offset:         248
        .size:           8
        .value_kind:     hidden_multigrid_sync_arg
      - .offset:         280
        .size:           4
        .value_kind:     hidden_dynamic_lds_size
    .group_segment_fixed_size: 0
    .kernarg_segment_align: 8
    .kernarg_segment_size: 416
    .language:       OpenCL C
    .language_version:
      - 2
      - 0
    .max_flat_workgroup_size: 512
    .name:           _Z14fwd_megakernel4Args
    .private_segment_fixed_size: 0
    .sgpr_count:     106
    .sgpr_spill_count: 155
    .symbol:         _Z14fwd_megakernel4Args.kd
    .uniform_work_group_size: 1
    .uses_dynamic_stack: false
    .vgpr_count:     256
    .vgpr_spill_count: 0
    .wavefront_size: 64
